# conv module: next tile's V/G rows prefetched right after the gating barrier so the loads overlap FIR and LayerNorm
# baseline (speedup 1.0000x reference)
.LBB7_803:
	s_or_b64 exec, exec, s[6:7]
	v_readlane_b32 s4, v252, 7
	v_readlane_b32 s5, v252, 8
	s_andn2_b64 vcc, exec, s[4:5]
	s_cbranch_vccnz .LBB7_813
	s_load_dwordx8 s[12:19], s[42:43], 0xa0
	v_readlane_b32 s4, v250, 10
	v_readlane_b32 s5, v250, 11
	s_lshl_b64 s[4:5], s[4:5], 2
	v_readlane_b32 s3, v250, 27
	s_waitcnt lgkmcnt(0)
	s_add_u32 s6, s18, s4
	s_addc_u32 s7, s19, s5
	s_add_u32 s8, s16, s4
	s_addc_u32 s9, s17, s5
	s_add_u32 s12, s12, s3
	s_movk_i32 s3, 0xba0
	s_addc_u32 s13, s13, 0
	v_cmp_gt_i32_e32 vcc, s3, v150
	s_movk_i32 s3, 0x180
	s_add_u32 s4, s14, s4
	v_cmp_gt_i32_e64 s[40:41], s3, v150
	v_ashrrev_i32_e32 v151, 31, v150
	v_lshlrev_b32_e32 v0, 2, v150
	v_readlane_b32 s3, v253, 39
	s_addc_u32 s5, s15, s5
	v_lshlrev_b64 v[2:3], 2, v[150:151]
	v_add_u32_e32 v108, 0, v0
	v_add_u32_e32 v109, s3, v0
	v_mov_b32_e32 v0, s3
	v_lshl_add_u64 v[10:11], s[4:5], 0, v[2:3]
	v_mad_u64_u32 v[12:13], s[4:5], v204, 24, v[0:1]
	v_lshl_add_u64 v[14:15], s[12:13], 0, v[2:3]
	s_mov_b64 s[4:5], 0x1200
	v_lshl_add_u64 v[16:17], v[14:15], 0, s[4:5]
	s_mov_b64 s[4:5], 0x1800
	v_lshl_add_u64 v[18:19], v[14:15], 0, s[4:5]
	s_mov_b64 s[4:5], 0x1e00
	v_lshl_add_u64 v[20:21], v[14:15], 0, s[4:5]
	s_mov_b64 s[4:5], 0x2400
	v_lshl_add_u64 v[22:23], v[14:15], 0, s[4:5]
	s_mov_b64 s[4:5], 0x2a00
	v_lshl_add_u64 v[24:25], v[14:15], 0, s[4:5]
	s_mov_b64 s[4:5], 0x3000
	v_lshl_add_u64 v[26:27], v[14:15], 0, s[4:5]
	s_mov_b64 s[4:5], 0x3600
	v_and_b32_e32 v0, 64, v163
	v_lshl_add_u64 v[28:29], v[14:15], 0, s[4:5]
	s_mov_b64 s[4:5], 0x3c00
	v_add_u32_e32 v0, 64, v0
	v_xor_b32_e32 v4, 1, v163
	v_lshl_add_u64 v[30:31], v[14:15], 0, s[4:5]
	s_mov_b64 s[4:5], 0x4200
	v_cmp_lt_i32_e64 s[42:43], v4, v0
	v_lshl_add_u64 v[32:33], v[14:15], 0, s[4:5]
	s_mov_b64 s[4:5], 0x4800
	v_cndmask_b32_e64 v4, v163, v4, s[42:43]
	v_lshl_add_u64 v[34:35], v[14:15], 0, s[4:5]
	s_mov_b64 s[4:5], 0x4e00
	v_lshlrev_b32_e32 v13, 2, v4
	v_xor_b32_e32 v4, 2, v163
	v_lshl_add_u64 v[36:37], v[14:15], 0, s[4:5]
	s_mov_b64 s[4:5], 0x5400
	v_cmp_lt_i32_e64 s[42:43], v4, v0
	v_lshl_add_u64 v[38:39], v[14:15], 0, s[4:5]
	s_mov_b64 s[4:5], 0x5a00
	v_cndmask_b32_e64 v4, v163, v4, s[42:43]
	v_lshl_add_u64 v[40:41], v[14:15], 0, s[4:5]
	s_mov_b64 s[4:5], 0x6000
	v_lshlrev_b32_e32 v110, 2, v4
	v_xor_b32_e32 v4, 4, v163
	v_lshl_add_u64 v[42:43], v[14:15], 0, s[4:5]
	s_mov_b64 s[4:5], 0x6600
	v_cmp_lt_i32_e64 s[42:43], v4, v0
	v_lshl_add_u64 v[44:45], v[14:15], 0, s[4:5]
	s_mov_b64 s[4:5], 0x6c00
	v_cndmask_b32_e64 v4, v163, v4, s[42:43]
	v_lshl_add_u64 v[46:47], v[14:15], 0, s[4:5]
	s_mov_b64 s[4:5], 0x7200
	v_lshlrev_b32_e32 v111, 2, v4
	v_xor_b32_e32 v4, 8, v163
	v_lshl_add_u64 v[48:49], v[14:15], 0, s[4:5]
	s_mov_b64 s[4:5], 0x7800
	v_cmp_lt_i32_e64 s[42:43], v4, v0
	v_lshl_add_u64 v[50:51], v[14:15], 0, s[4:5]
	s_mov_b64 s[4:5], 0x7e00
	v_cndmask_b32_e64 v4, v163, v4, s[42:43]
	v_lshl_add_u64 v[52:53], v[14:15], 0, s[4:5]
	s_mov_b64 s[4:5], 0x8400
	v_lshlrev_b32_e32 v112, 2, v4
	v_xor_b32_e32 v4, 16, v163
	v_lshl_add_u64 v[54:55], v[14:15], 0, s[4:5]
	s_mov_b64 s[4:5], 0x8a00
	v_cmp_lt_i32_e64 s[42:43], v4, v0
	v_lshl_add_u64 v[56:57], v[14:15], 0, s[4:5]
	s_mov_b64 s[4:5], 0x9000
	v_cndmask_b32_e64 v4, v163, v4, s[42:43]
	v_lshl_add_u64 v[58:59], v[14:15], 0, s[4:5]
	s_mov_b64 s[4:5], 0x9600
	v_lshlrev_b32_e32 v113, 2, v4
	v_xor_b32_e32 v4, 32, v163
	v_lshl_add_u64 v[60:61], v[14:15], 0, s[4:5]
	s_mov_b64 s[4:5], 0x9c00
	v_cmp_lt_i32_e64 s[42:43], v4, v0
	v_lshl_add_u64 v[62:63], v[14:15], 0, s[4:5]
	s_mov_b64 s[4:5], 0xa200
	v_cndmask_b32_e64 v0, v163, v4, s[42:43]
	v_mul_lo_u32 v4, v204, 6
	v_lshl_add_u64 v[64:65], v[14:15], 0, s[4:5]
	s_mov_b64 s[4:5], 0xa800
	v_ashrrev_i32_e32 v5, 31, v4
	v_lshl_add_u64 v[66:67], v[14:15], 0, s[4:5]
	s_mov_b64 s[4:5], 0xae00
	v_lshl_add_u64 v[68:69], v[14:15], 0, s[4:5]
	s_mov_b64 s[4:5], 0xb400
	v_lshlrev_b64 v[2:3], 2, v[4:5]
	v_lshlrev_b32_e32 v114, 2, v0
	v_lshl_add_u64 v[70:71], v[14:15], 0, s[4:5]
	v_add_u32_e32 v115, 0x10200, v108
	v_add_u32_e32 v116, 0x10800, v108
	v_add_u32_e32 v117, 0x10e00, v108
	v_add_u32_e32 v118, 0x11400, v108
	v_add_u32_e32 v119, 0x11a00, v108
	v_add_u32_e32 v120, 0x12000, v108
	v_add_u32_e32 v121, 0x12600, v108
	v_add_u32_e32 v122, 0x12c00, v108
	v_add_u32_e32 v123, 0x13200, v108
	v_add_u32_e32 v124, 0x13800, v108
	v_add_u32_e32 v125, 0x13e00, v108
	v_add_u32_e32 v126, 0x14400, v108
	v_add_u32_e32 v127, 0x14a00, v108
	v_add_u32_e32 v128, 0x15000, v108
	v_add_u32_e32 v129, 0x15600, v108
	v_add_u32_e32 v130, 0x15c00, v108
	v_add_u32_e32 v131, 0x16200, v108
	v_add_u32_e32 v132, 0x16800, v108
	v_add_u32_e32 v133, 0x16e00, v108
	v_lshl_add_u64 v[72:73], s[8:9], 0, v[2:3]
	v_lshl_add_u64 v[74:75], s[6:7], 0, v[2:3]
	v_lshl_add_u64 v[76:77], v[4:5], 1, s[0:1]
	s_and_saveexec_b64 s[4:5], s[40:41]
	global_load_dword v247, v[10:11], off
	global_load_dword v216, v[14:15], off
	global_load_dword v217, v[14:15], off offset:1536
	global_load_dword v218, v[14:15], off offset:3072
	global_load_dword v219, v[16:17], off
	global_load_dword v220, v[18:19], off
	global_load_dword v221, v[20:21], off
	global_load_dword v222, v[22:23], off
	global_load_dword v223, v[24:25], off
	global_load_dword v224, v[26:27], off
	global_load_dword v225, v[28:29], off
	global_load_dword v226, v[30:31], off
	global_load_dword v227, v[32:33], off
	global_load_dword v228, v[34:35], off
	global_load_dword v229, v[36:37], off
	global_load_dword v230, v[38:39], off
	global_load_dword v231, v[40:41], off
	global_load_dword v232, v[42:43], off
	global_load_dword v233, v[44:45], off
	global_load_dword v234, v[46:47], off
	global_load_dword v235, v[48:49], off
	global_load_dword v236, v[50:51], off
	global_load_dword v237, v[52:53], off
	global_load_dword v238, v[54:55], off
	global_load_dword v239, v[56:57], off
	global_load_dword v240, v[58:59], off
	global_load_dword v241, v[60:61], off
	global_load_dword v242, v[62:63], off
	global_load_dword v243, v[64:65], off
	global_load_dword v244, v[66:67], off
	global_load_dword v245, v[68:69], off
	global_load_dword v246, v[70:71], off
	s_or_b64 exec, exec, s[4:5]
	s_waitcnt vmcnt(0)
	global_load_dwordx4 v[14:17], v[72:73], off
	global_load_dwordx2 v[18:19], v[72:73], off offset:16
	global_load_dwordx4 v[20:23], v[74:75], off
	global_load_dwordx2 v[10:11], v[74:75], off offset:16
	s_waitcnt vmcnt(0)
	s_mov_b32 s12, s2
	s_movk_i32 s14, 0x1a0
	v_cmp_gt_i32_e64 s[6:7], s14, v150
	s_lshl_b32 s15, s12, 5
	s_and_b32 s3, s15, 0x7e0
	s_sub_i32 s3, 29, s3
	s_sub_i32 s4, s15, 30
	s_mov_b32 s5, 0x2aaaaaab
	s_movk_i32 s14, 0xfe80
	v_mov_b32_e32 v79, v150
	v_mul_hi_i32 v80, v79, s5
	v_lshrrev_b32_e32 v81, 31, v80
	v_ashrrev_i32_e32 v80, 3, v80
	v_add_u32_e32 v80, v80, v81
	v_cmp_lt_i32_e64 s[42:43], s3, v80
	s_nop 1
	s_and_saveexec_b64 s[8:9], s[42:43]
	v_add_u32_e32 v82, s4, v80
	v_ashrrev_i32_e32 v83, 31, v82
	v_lshlrev_b64 v[82:83], 11, v[82:83]
	v_lshl_add_u64 v[82:83], s[44:45], 0, v[82:83]
	v_lshlrev_b32_e32 v84, 3, v79
	v_mad_i32_i24 v84, v80, s14, v84
	v_mov_b32_e32 v85, 0
	v_lshl_add_u64 v[82:83], v[84:85], 1, v[82:83]
	global_load_dwordx4 v[24:27], v[82:83], off offset:512
	global_load_dwordx4 v[28:31], v[82:83], off offset:1280
	s_or_b64 exec, exec, s[8:9]
	v_add_u32_e32 v79, 512, v150
	v_mul_hi_i32 v80, v79, s5
	v_lshrrev_b32_e32 v81, 31, v80
	v_ashrrev_i32_e32 v80, 3, v80
	v_add_u32_e32 v80, v80, v81
	v_cmp_lt_i32_e64 s[42:43], s3, v80
	s_nop 1
	s_and_saveexec_b64 s[8:9], s[42:43]
	v_add_u32_e32 v82, s4, v80
	v_ashrrev_i32_e32 v83, 31, v82
	v_lshlrev_b64 v[82:83], 11, v[82:83]
	v_lshl_add_u64 v[82:83], s[44:45], 0, v[82:83]
	v_lshlrev_b32_e32 v84, 3, v79
	v_mad_i32_i24 v84, v80, s14, v84
	v_mov_b32_e32 v85, 0
	v_lshl_add_u64 v[82:83], v[84:85], 1, v[82:83]
	global_load_dwordx4 v[32:35], v[82:83], off offset:512
	global_load_dwordx4 v[36:39], v[82:83], off offset:1280
	s_or_b64 exec, exec, s[8:9]
	v_add_u32_e32 v79, 1024, v150
	v_mul_hi_i32 v80, v79, s5
	v_lshrrev_b32_e32 v81, 31, v80
	v_ashrrev_i32_e32 v80, 3, v80
	v_add_u32_e32 v80, v80, v81
	v_cmp_lt_i32_e64 s[42:43], s3, v80
	s_nop 1
	s_and_saveexec_b64 s[8:9], s[42:43]
	v_add_u32_e32 v82, s4, v80
	v_ashrrev_i32_e32 v83, 31, v82
	v_lshlrev_b64 v[82:83], 11, v[82:83]
	v_lshl_add_u64 v[82:83], s[44:45], 0, v[82:83]
	v_lshlrev_b32_e32 v84, 3, v79
	v_mad_i32_i24 v84, v80, s14, v84
	v_mov_b32_e32 v85, 0
	v_lshl_add_u64 v[82:83], v[84:85], 1, v[82:83]
	global_load_dwordx4 v[40:43], v[82:83], off offset:512
	global_load_dwordx4 v[44:47], v[82:83], off offset:1280
	s_or_b64 exec, exec, s[8:9]
	v_add_u32_e32 v79, 1536, v150
	v_mul_hi_i32 v80, v79, s5
	v_lshrrev_b32_e32 v81, 31, v80
	v_ashrrev_i32_e32 v80, 3, v80
	v_add_u32_e32 v80, v80, v81
	v_cmp_lt_i32_e64 s[42:43], s3, v80
	s_nop 1
	s_and_saveexec_b64 s[8:9], s[42:43]
	v_add_u32_e32 v82, s4, v80
	v_ashrrev_i32_e32 v83, 31, v82
	v_lshlrev_b64 v[82:83], 11, v[82:83]
	v_lshl_add_u64 v[82:83], s[44:45], 0, v[82:83]
	v_lshlrev_b32_e32 v84, 3, v79
	v_mad_i32_i24 v84, v80, s14, v84
	v_mov_b32_e32 v85, 0
	v_lshl_add_u64 v[82:83], v[84:85], 1, v[82:83]
	global_load_dwordx4 v[48:51], v[82:83], off offset:512
	global_load_dwordx4 v[52:55], v[82:83], off offset:1280
	s_or_b64 exec, exec, s[8:9]
	v_add_u32_e32 v79, 2048, v150
	v_mul_hi_i32 v80, v79, s5
	v_lshrrev_b32_e32 v81, 31, v80
	v_ashrrev_i32_e32 v80, 3, v80
	v_add_u32_e32 v80, v80, v81
	v_cmp_lt_i32_e64 s[42:43], s3, v80
	s_nop 1
	s_and_saveexec_b64 s[8:9], s[42:43]
	v_add_u32_e32 v82, s4, v80
	v_ashrrev_i32_e32 v83, 31, v82
	v_lshlrev_b64 v[82:83], 11, v[82:83]
	v_lshl_add_u64 v[82:83], s[44:45], 0, v[82:83]
	v_lshlrev_b32_e32 v84, 3, v79
	v_mad_i32_i24 v84, v80, s14, v84
	v_mov_b32_e32 v85, 0
	v_lshl_add_u64 v[82:83], v[84:85], 1, v[82:83]
	global_load_dwordx4 v[56:59], v[82:83], off offset:512
	global_load_dwordx4 v[60:63], v[82:83], off offset:1280
	s_or_b64 exec, exec, s[8:9]
	v_add_u32_e32 v79, 2560, v150
	v_mul_hi_i32 v80, v79, s5
	v_lshrrev_b32_e32 v81, 31, v80
	v_ashrrev_i32_e32 v80, 3, v80
	v_add_u32_e32 v80, v80, v81
	v_cmp_lt_i32_e64 s[42:43], s3, v80
	s_nop 1
	s_and_b64 s[42:43], s[42:43], s[6:7]
	s_and_saveexec_b64 s[8:9], s[42:43]
	v_add_u32_e32 v82, s4, v80
	v_ashrrev_i32_e32 v83, 31, v82
	v_lshlrev_b64 v[82:83], 11, v[82:83]
	v_lshl_add_u64 v[82:83], s[44:45], 0, v[82:83]
	v_lshlrev_b32_e32 v84, 3, v79
	v_mad_i32_i24 v84, v80, s14, v84
	v_mov_b32_e32 v85, 0
	v_lshl_add_u64 v[82:83], v[84:85], 1, v[82:83]
	global_load_dwordx4 v[64:67], v[82:83], off offset:512
	global_load_dwordx4 v[68:71], v[82:83], off offset:1280
	s_or_b64 exec, exec, s[8:9]
	s_branch .LBB7_806
.LBB7_805:
	s_or_b64 exec, exec, s[0:1]
	v_add_u32_e32 v0, s31, v12
	s_waitcnt lgkmcnt(0)
	s_barrier
	ds_read2_b64 v[2:5], v0 offset1:1
	s_add_i32 s0, s13, s86
	s_ashr_i32 s1, s0, 31
	s_lshl_b64 s[0:1], s[0:1], 11
	s_add_i32 s12, s12, s60
	s_waitcnt lgkmcnt(0)
	v_add_f32_e32 v6, 0, v2
	v_add_f32_e32 v8, v6, v3
	ds_read_b64 v[6:7], v0 offset:16
	v_add_f32_e32 v0, v8, v4
	v_add_f32_e32 v0, v0, v5
	s_waitcnt lgkmcnt(0)
	v_add_f32_e32 v0, v0, v6
	v_add_f32_e32 v0, v0, v7
	s_nop 0
	s_waitcnt lgkmcnt(0)
	s_nop 1
	v_add_f32_dpp v0, v0, v0 quad_perm:[1,0,3,2] row_mask:0xf bank_mask:0xf
	s_nop 0
	s_waitcnt lgkmcnt(0)
	s_nop 1
	v_add_f32_dpp v0, v0, v0 quad_perm:[2,3,0,1] row_mask:0xf bank_mask:0xf
	s_nop 0
	s_waitcnt lgkmcnt(0)
	s_nop 1
	v_add_f32_dpp v0, v0, v0 row_half_mirror row_mask:0xf bank_mask:0xf
	s_nop 0
	s_waitcnt lgkmcnt(0)
	s_nop 1
	v_add_f32_dpp v0, v0, v0 row_mirror row_mask:0xf bank_mask:0xf
	v_mov_b32_e32 v8, v0
	s_nop 1
	v_permlane16_swap_b32_e32 v0, v8
	s_waitcnt lgkmcnt(0)
	v_add_f32_e32 v0, v0, v8
	v_mov_b32_e32 v8, v0
	s_nop 1
	v_permlane32_swap_b32_e32 v0, v8
	s_waitcnt lgkmcnt(0)
	v_add_f32_e32 v8, v0, v8
	v_mul_f32_e32 v0, 0x3b2aaaab, v8
	v_fmac_f32_e32 v3, 0xbb2aaaab, v8
	v_fmamk_f32 v2, v8, 0xbb2aaaab, v2
	v_mul_f32_e32 v78, v3, v3
	v_pk_add_f32 v[8:9], v[4:5], v[0:1] op_sel_hi:[1,0] neg_lo:[0,1] neg_hi:[0,1]
	v_fmac_f32_e32 v78, v2, v2
	v_pk_mul_f32 v[4:5], v[8:9], v[8:9]
	v_pk_add_f32 v[82:83], v[6:7], v[0:1] op_sel_hi:[1,0] neg_lo:[0,1] neg_hi:[0,1]
	v_add_f32_e32 v4, v4, v78
	v_add_f32_e32 v78, v5, v4
	v_pk_mul_f32 v[4:5], v[82:83], v[82:83]
	s_nop 0
	v_add_f32_e32 v0, v4, v78
	v_add_f32_e32 v0, v5, v0
	s_nop 0
	s_waitcnt lgkmcnt(0)
	s_nop 1
	v_add_f32_dpp v0, v0, v0 quad_perm:[1,0,3,2] row_mask:0xf bank_mask:0xf
	s_nop 0
	s_waitcnt lgkmcnt(0)
	s_nop 1
	v_add_f32_dpp v0, v0, v0 quad_perm:[2,3,0,1] row_mask:0xf bank_mask:0xf
	s_nop 0
	s_waitcnt lgkmcnt(0)
	s_nop 1
	v_add_f32_dpp v0, v0, v0 row_half_mirror row_mask:0xf bank_mask:0xf
	s_nop 0
	s_waitcnt lgkmcnt(0)
	s_nop 1
	v_add_f32_dpp v0, v0, v0 row_mirror row_mask:0xf bank_mask:0xf
	v_mov_b32_e32 v4, v0
	s_nop 1
	v_permlane16_swap_b32_e32 v0, v4
	s_waitcnt lgkmcnt(0)
	v_add_f32_e32 v0, v0, v4
	v_mov_b32_e32 v4, v0
	s_nop 1
	v_permlane32_swap_b32_e32 v0, v4
	s_waitcnt lgkmcnt(0)
	v_add_f32_e32 v0, v0, v4
	v_fmamk_f32 v0, v0, 0x3b2aaaab, v162
	v_cmp_gt_f32_e64 s[42:43], s11, v0
	v_mul_f32_e32 v4, 0x4b800000, v0
	s_nop 0
	v_cndmask_b32_e64 v0, v0, v4, s[42:43]
	v_rsq_f32_e32 v0, v0
	s_nop 0
	v_mul_f32_e32 v4, 0x45800000, v0
	v_cndmask_b32_e64 v0, v0, v4, s[42:43]
	v_mul_f32_e32 v2, v2, v0
	v_fma_f32 v2, v14, v2, v20
	v_mul_f32_e32 v4, 0xbfb8aa3b, v2
	v_exp_f32_e32 v4, v4
	s_nop 0
	v_add_f32_e32 v4, 1.0, v4
	v_rcp_f32_e32 v4, v4
	s_nop 0
	v_mul_f32_e32 v4, v2, v4
	v_mul_f32_e32 v2, v3, v0
	v_fma_f32 v2, v15, v2, v21
	v_mul_f32_e32 v3, 0xbfb8aa3b, v2
	v_exp_f32_e32 v3, v3
	s_nop 0
	v_add_f32_e32 v3, 1.0, v3
	v_rcp_f32_e32 v3, v3
	s_nop 0
	v_mul_f32_e32 v5, v2, v3
	v_mul_f32_e32 v2, v8, v0
	v_fma_f32 v2, v16, v2, v22
	v_mul_f32_e32 v3, 0xbfb8aa3b, v2
	v_exp_f32_e32 v3, v3
	v_cvt_pk_bf16_f32 v4, v4, v5
	s_nop 0
	v_add_f32_e32 v3, 1.0, v3
	v_rcp_f32_e32 v3, v3
	s_nop 0
	v_mul_f32_e32 v6, v2, v3
	v_mul_f32_e32 v2, v9, v0
	v_fma_f32 v81, v17, v2, v23
	v_mul_f32_e32 v2, 0xbfb8aa3b, v81
	v_exp_f32_e32 v2, v2
	s_nop 0
	v_add_f32_e32 v2, 1.0, v2
	v_rcp_f32_e32 v2, v2
	s_nop 0
	v_mul_f32_e32 v7, v81, v2
	v_mul_f32_e32 v2, v82, v0
	v_mul_f32_e32 v0, v83, v0
	v_fma_f32 v2, v18, v2, v10
	v_fma_f32 v87, v19, v0, v11
	v_mul_f32_e32 v3, 0xbfb8aa3b, v2
	v_mul_f32_e32 v0, 0xbfb8aa3b, v87
	v_exp_f32_e32 v3, v3
	v_exp_f32_e32 v0, v0
	v_add_f32_e32 v3, 1.0, v3
	v_add_f32_e32 v0, 1.0, v0
	v_rcp_f32_e32 v3, v3
	v_rcp_f32_e32 v0, v0
	v_mul_f32_e32 v8, v2, v3
	v_mul_f32_e32 v0, v87, v0
	v_lshl_add_u64 v[2:3], v[76:77], 0, s[0:1]
	global_store_dword v[2:3], v4, off offset:1280
	v_cvt_pk_bf16_f32 v4, v6, v7
	global_store_dword v[2:3], v4, off offset:1284
	v_cvt_pk_bf16_f32 v0, v8, v0
	s_mul_i32 s0, s91, 0x600
	global_store_dword v[2:3], v0, off offset:1288
	v_add_u32_e32 v0, s0, v12
	ds_read2_b64 v[2:5], v0 offset1:1
	s_add_i32 s0, s13, s91
	s_ashr_i32 s1, s0, 31
	s_lshl_b64 s[0:1], s[0:1], 11
	s_waitcnt lgkmcnt(0)
	v_add_f32_e32 v6, 0, v2
	v_add_f32_e32 v8, v6, v3
	ds_read_b64 v[6:7], v0 offset:16
	v_add_f32_e32 v8, v8, v4
	v_add_f32_e32 v8, v8, v5
	s_waitcnt lgkmcnt(0)
	v_add_f32_e32 v8, v8, v6
	v_add_f32_e32 v8, v8, v7
	s_nop 0
	s_waitcnt lgkmcnt(0)
	s_nop 1
	v_add_f32_dpp v8, v8, v8 quad_perm:[1,0,3,2] row_mask:0xf bank_mask:0xf
	s_nop 0
	s_waitcnt lgkmcnt(0)
	s_nop 1
	v_add_f32_dpp v8, v8, v8 quad_perm:[2,3,0,1] row_mask:0xf bank_mask:0xf
	s_nop 0
	s_waitcnt lgkmcnt(0)
	s_nop 1
	v_add_f32_dpp v8, v8, v8 row_half_mirror row_mask:0xf bank_mask:0xf
	s_nop 0
	s_waitcnt lgkmcnt(0)
	s_nop 1
	v_add_f32_dpp v8, v8, v8 row_mirror row_mask:0xf bank_mask:0xf
	v_mov_b32_e32 v9, v8
	s_nop 1
	v_permlane16_swap_b32_e32 v8, v9
	s_waitcnt lgkmcnt(0)
	v_add_f32_e32 v8, v8, v9
	v_mov_b32_e32 v9, v8
	s_nop 1
	v_permlane32_swap_b32_e32 v8, v9
	s_waitcnt lgkmcnt(0)
	v_add_f32_e32 v9, v8, v9
	v_fmac_f32_e32 v3, 0xbb2aaaab, v9
	v_mul_f32_e32 v8, 0x3b2aaaab, v9
	v_fmamk_f32 v2, v9, 0xbb2aaaab, v2
	v_mul_f32_e32 v9, v3, v3
	v_fmac_f32_e32 v9, v2, v2
	v_pk_add_f32 v[82:83], v[4:5], v[8:9] op_sel_hi:[1,0] neg_lo:[0,1] neg_hi:[0,1]
	s_nop 0
	v_pk_mul_f32 v[4:5], v[82:83], v[82:83]
	s_nop 0
	v_add_f32_e32 v4, v4, v9
	v_pk_add_f32 v[8:9], v[6:7], v[8:9] op_sel_hi:[1,0] neg_lo:[0,1] neg_hi:[0,1]
	v_add_f32_e32 v78, v5, v4
	v_pk_mul_f32 v[4:5], v[8:9], v[8:9]
	s_nop 0
	v_add_f32_e32 v4, v4, v78
	v_add_f32_e32 v4, v5, v4
	s_nop 0
	s_waitcnt lgkmcnt(0)
	s_nop 1
	v_add_f32_dpp v4, v4, v4 quad_perm:[1,0,3,2] row_mask:0xf bank_mask:0xf
	s_nop 0
	s_waitcnt lgkmcnt(0)
	s_nop 1
	v_add_f32_dpp v4, v4, v4 quad_perm:[2,3,0,1] row_mask:0xf bank_mask:0xf
	s_nop 0
	s_waitcnt lgkmcnt(0)
	s_nop 1
	v_add_f32_dpp v4, v4, v4 row_half_mirror row_mask:0xf bank_mask:0xf
	s_nop 0
	s_waitcnt lgkmcnt(0)
	s_nop 1
	v_add_f32_dpp v4, v4, v4 row_mirror row_mask:0xf bank_mask:0xf
	v_mov_b32_e32 v5, v4
	s_nop 1
	v_permlane16_swap_b32_e32 v4, v5
	s_waitcnt lgkmcnt(0)
	v_add_f32_e32 v4, v4, v5
	v_mov_b32_e32 v5, v4
	s_nop 1
	v_permlane32_swap_b32_e32 v4, v5
	s_waitcnt lgkmcnt(0)
	v_add_f32_e32 v4, v4, v5
	v_fmamk_f32 v4, v4, 0x3b2aaaab, v162
	v_cmp_gt_f32_e64 s[42:43], s11, v4
	v_mul_f32_e32 v5, 0x4b800000, v4
	s_nop 0
	v_cndmask_b32_e64 v4, v4, v5, s[42:43]
	v_rsq_f32_e32 v4, v4
	s_nop 0
	v_mul_f32_e32 v5, 0x45800000, v4
	v_cndmask_b32_e64 v88, v4, v5, s[42:43]
	v_mul_f32_e32 v2, v2, v88
	v_mul_f32_e32 v3, v3, v88
	v_fma_f32 v2, v14, v2, v20
	v_mul_f32_e32 v4, 0xbfb8aa3b, v2
	v_exp_f32_e32 v4, v4
	v_fma_f32 v3, v15, v3, v21
	v_add_f32_e32 v4, 1.0, v4
	v_rcp_f32_e32 v4, v4
	s_nop 0
	v_mul_f32_e32 v2, v2, v4
	v_mul_f32_e32 v4, 0xbfb8aa3b, v3
	v_exp_f32_e32 v4, v4
	s_nop 0
	v_add_f32_e32 v4, 1.0, v4
	v_rcp_f32_e32 v4, v4
	s_nop 0
	v_mul_f32_e32 v3, v3, v4
	v_mul_f32_e32 v4, v82, v88
	v_fma_f32 v4, v16, v4, v22
	v_mul_f32_e32 v5, 0xbfb8aa3b, v4
	v_exp_f32_e32 v5, v5
	v_mul_f32_e32 v6, v8, v88
	v_fma_f32 v6, v18, v6, v10
	v_cvt_pk_bf16_f32 v2, v2, v3
	v_add_f32_e32 v5, 1.0, v5
	v_rcp_f32_e32 v5, v5
	s_nop 0
	v_mul_f32_e32 v4, v4, v5
	v_mul_f32_e32 v5, v83, v88
	v_fma_f32 v81, v17, v5, v23
	v_mul_f32_e32 v7, 0xbfb8aa3b, v6
	v_exp_f32_e32 v7, v7
	v_mul_f32_e32 v5, 0xbfb8aa3b, v81
	v_exp_f32_e32 v5, v5
	v_add_f32_e32 v7, 1.0, v7
	v_rcp_f32_e32 v7, v7
	v_add_f32_e32 v5, 1.0, v5
	v_rcp_f32_e32 v5, v5
	v_mul_f32_e32 v6, v6, v7
	v_mul_f32_e32 v7, v9, v88
	v_fma_f32 v87, v19, v7, v11
	v_mul_f32_e32 v7, 0xbfb8aa3b, v87
	v_exp_f32_e32 v7, v7
	v_lshl_add_u64 v[8:9], v[76:77], 0, s[0:1]
	v_mul_f32_e32 v5, v81, v5
	global_store_dword v[8:9], v2, off offset:1280
	v_add_f32_e32 v7, 1.0, v7
	v_rcp_f32_e32 v7, v7
	v_cvt_pk_bf16_f32 v2, v4, v5
	global_store_dword v[8:9], v2, off offset:1284
	s_add_i32 s0, s13, s93
	v_mul_f32_e32 v7, v87, v7
	v_cvt_pk_bf16_f32 v2, v6, v7
	global_store_dword v[8:9], v2, off offset:1288
	ds_read2_b64 v[2:5], v0 offset0:192 offset1:193
	s_ashr_i32 s1, s0, 31
	s_lshl_b64 s[0:1], s[0:1], 11
	s_waitcnt lgkmcnt(0)
	v_add_f32_e32 v6, 0, v2
	v_add_f32_e32 v8, v6, v3
	ds_read_b64 v[6:7], v0 offset:1552
	v_add_f32_e32 v8, v8, v4
	v_add_f32_e32 v8, v8, v5
	s_waitcnt lgkmcnt(0)
	v_add_f32_e32 v8, v8, v6
	v_add_f32_e32 v8, v8, v7
	s_nop 0
	s_waitcnt lgkmcnt(0)
	s_nop 1
	v_add_f32_dpp v8, v8, v8 quad_perm:[1,0,3,2] row_mask:0xf bank_mask:0xf
	s_nop 0
	s_waitcnt lgkmcnt(0)
	s_nop 1
	v_add_f32_dpp v8, v8, v8 quad_perm:[2,3,0,1] row_mask:0xf bank_mask:0xf
	s_nop 0
	s_waitcnt lgkmcnt(0)
	s_nop 1
	v_add_f32_dpp v8, v8, v8 row_half_mirror row_mask:0xf bank_mask:0xf
	s_nop 0
	s_waitcnt lgkmcnt(0)
	s_nop 1
	v_add_f32_dpp v8, v8, v8 row_mirror row_mask:0xf bank_mask:0xf
	v_mov_b32_e32 v9, v8
	s_nop 1
	v_permlane16_swap_b32_e32 v8, v9
	s_waitcnt lgkmcnt(0)
	v_add_f32_e32 v8, v8, v9
	v_mov_b32_e32 v9, v8
	s_nop 1
	v_permlane32_swap_b32_e32 v8, v9
	s_waitcnt lgkmcnt(0)
	v_add_f32_e32 v9, v8, v9
	v_fmac_f32_e32 v3, 0xbb2aaaab, v9
	v_mul_f32_e32 v8, 0x3b2aaaab, v9
	v_fmamk_f32 v2, v9, 0xbb2aaaab, v2
	v_mul_f32_e32 v9, v3, v3
	v_fmac_f32_e32 v9, v2, v2
	v_pk_add_f32 v[82:83], v[4:5], v[8:9] op_sel_hi:[1,0] neg_lo:[0,1] neg_hi:[0,1]
	s_nop 0
	v_pk_mul_f32 v[4:5], v[82:83], v[82:83]
	s_nop 0
	v_add_f32_e32 v4, v4, v9
	v_pk_add_f32 v[8:9], v[6:7], v[8:9] op_sel_hi:[1,0] neg_lo:[0,1] neg_hi:[0,1]
	v_add_f32_e32 v78, v5, v4
	v_pk_mul_f32 v[4:5], v[8:9], v[8:9]
	s_nop 0
	v_add_f32_e32 v4, v4, v78
	v_add_f32_e32 v4, v5, v4
	s_nop 0
	s_waitcnt lgkmcnt(0)
	s_nop 1
	v_add_f32_dpp v4, v4, v4 quad_perm:[1,0,3,2] row_mask:0xf bank_mask:0xf
	s_nop 0
	s_waitcnt lgkmcnt(0)
	s_nop 1
	v_add_f32_dpp v4, v4, v4 quad_perm:[2,3,0,1] row_mask:0xf bank_mask:0xf
	s_nop 0
	s_waitcnt lgkmcnt(0)
	s_nop 1
	v_add_f32_dpp v4, v4, v4 row_half_mirror row_mask:0xf bank_mask:0xf
	s_nop 0
	s_waitcnt lgkmcnt(0)
	s_nop 1
	v_add_f32_dpp v4, v4, v4 row_mirror row_mask:0xf bank_mask:0xf
	v_mov_b32_e32 v5, v4
	s_nop 1
	v_permlane16_swap_b32_e32 v4, v5
	s_waitcnt lgkmcnt(0)
	v_add_f32_e32 v4, v4, v5
	v_mov_b32_e32 v5, v4
	s_nop 1
	v_permlane32_swap_b32_e32 v4, v5
	s_waitcnt lgkmcnt(0)
	v_add_f32_e32 v4, v4, v5
	v_fmamk_f32 v4, v4, 0x3b2aaaab, v162
	v_cmp_gt_f32_e64 s[42:43], s11, v4
	v_mul_f32_e32 v5, 0x4b800000, v4
	s_nop 0
	v_cndmask_b32_e64 v4, v4, v5, s[42:43]
	v_rsq_f32_e32 v4, v4
	s_nop 0
	v_mul_f32_e32 v5, 0x45800000, v4
	v_cndmask_b32_e64 v88, v4, v5, s[42:43]
	v_mul_f32_e32 v2, v2, v88
	v_fma_f32 v2, v14, v2, v20
	v_mul_f32_e32 v4, 0xbfb8aa3b, v2
	v_exp_f32_e32 v4, v4
	s_nop 0
	v_add_f32_e32 v4, 1.0, v4
	v_rcp_f32_e32 v4, v4
	s_nop 0
	v_mul_f32_e32 v4, v2, v4
	v_mul_f32_e32 v2, v3, v88
	v_fma_f32 v2, v15, v2, v21
	v_mul_f32_e32 v3, 0xbfb8aa3b, v2
	v_exp_f32_e32 v3, v3
	s_nop 0
	v_add_f32_e32 v3, 1.0, v3
	v_rcp_f32_e32 v3, v3
	s_nop 0
	v_mul_f32_e32 v5, v2, v3
	v_mul_f32_e32 v2, v82, v88
	v_fma_f32 v2, v16, v2, v22
	v_mul_f32_e32 v3, 0xbfb8aa3b, v2
	v_exp_f32_e32 v3, v3
	v_cvt_pk_bf16_f32 v4, v4, v5
	s_nop 0
	v_add_f32_e32 v3, 1.0, v3
	v_rcp_f32_e32 v3, v3
	s_nop 0
	v_mul_f32_e32 v6, v2, v3
	v_mul_f32_e32 v2, v83, v88
	v_fma_f32 v81, v17, v2, v23
	v_mul_f32_e32 v2, 0xbfb8aa3b, v81
	v_exp_f32_e32 v2, v2
	s_nop 0
	v_add_f32_e32 v2, 1.0, v2
	v_rcp_f32_e32 v2, v2
	s_nop 0
	v_mul_f32_e32 v7, v81, v2
	v_mul_f32_e32 v2, v8, v88
	v_fma_f32 v2, v18, v2, v10
	v_mul_f32_e32 v3, 0xbfb8aa3b, v2
	v_exp_f32_e32 v3, v3
	s_nop 0
	v_add_f32_e32 v3, 1.0, v3
	v_rcp_f32_e32 v3, v3
	s_nop 0
	v_mul_f32_e32 v8, v2, v3
	v_mul_f32_e32 v2, v9, v88
	v_fma_f32 v87, v19, v2, v11
	v_mul_f32_e32 v2, 0xbfb8aa3b, v87
	v_exp_f32_e32 v2, v2
	s_nop 0
	v_add_f32_e32 v2, 1.0, v2
	v_rcp_f32_e32 v2, v2
	s_nop 0
	v_mul_f32_e32 v9, v87, v2
	v_lshl_add_u64 v[2:3], v[76:77], 0, s[0:1]
	global_store_dword v[2:3], v4, off offset:1280
	v_cvt_pk_bf16_f32 v4, v6, v7
	global_store_dword v[2:3], v4, off offset:1284
	v_cvt_pk_bf16_f32 v4, v8, v9
	global_store_dword v[2:3], v4, off offset:1288
	v_add_u32_e32 v2, 0xc00, v0
	ds_read2_b64 v[2:5], v2 offset1:1
	s_add_i32 s0, s13, s28
	s_ashr_i32 s1, s0, 31
	s_lshl_b64 s[0:1], s[0:1], 11
	s_cmpk_lt_i32 s12, 0x400
	s_waitcnt lgkmcnt(0)
	v_add_f32_e32 v6, 0, v2
	v_add_f32_e32 v8, v6, v3
	ds_read_b64 v[6:7], v0 offset:3088
	v_add_f32_e32 v0, v8, v4
	v_add_f32_e32 v0, v0, v5
	s_waitcnt lgkmcnt(0)
	v_add_f32_e32 v0, v0, v6
	v_add_f32_e32 v0, v0, v7
	s_nop 0
	s_waitcnt lgkmcnt(0)
	s_nop 1
	v_add_f32_dpp v0, v0, v0 quad_perm:[1,0,3,2] row_mask:0xf bank_mask:0xf
	s_nop 0
	s_waitcnt lgkmcnt(0)
	s_nop 1
	v_add_f32_dpp v0, v0, v0 quad_perm:[2,3,0,1] row_mask:0xf bank_mask:0xf
	s_nop 0
	s_waitcnt lgkmcnt(0)
	s_nop 1
	v_add_f32_dpp v0, v0, v0 row_half_mirror row_mask:0xf bank_mask:0xf
	s_nop 0
	s_waitcnt lgkmcnt(0)
	s_nop 1
	v_add_f32_dpp v0, v0, v0 row_mirror row_mask:0xf bank_mask:0xf
	v_mov_b32_e32 v8, v0
	s_nop 1
	v_permlane16_swap_b32_e32 v0, v8
	s_waitcnt lgkmcnt(0)
	v_add_f32_e32 v0, v0, v8
	v_mov_b32_e32 v8, v0
	s_nop 1
	v_permlane32_swap_b32_e32 v0, v8
	s_waitcnt lgkmcnt(0)
	v_add_f32_e32 v8, v0, v8
	v_mul_f32_e32 v0, 0x3b2aaaab, v8
	v_fmac_f32_e32 v3, 0xbb2aaaab, v8
	v_fmamk_f32 v2, v8, 0xbb2aaaab, v2
	v_mul_f32_e32 v78, v3, v3
	v_pk_add_f32 v[8:9], v[4:5], v[0:1] op_sel_hi:[1,0] neg_lo:[0,1] neg_hi:[0,1]
	v_fmac_f32_e32 v78, v2, v2
	v_pk_mul_f32 v[4:5], v[8:9], v[8:9]
	v_pk_add_f32 v[82:83], v[6:7], v[0:1] op_sel_hi:[1,0] neg_lo:[0,1] neg_hi:[0,1]
	v_add_f32_e32 v4, v4, v78
	v_add_f32_e32 v78, v5, v4
	v_pk_mul_f32 v[4:5], v[82:83], v[82:83]
	s_nop 0
	v_add_f32_e32 v0, v4, v78
	v_add_f32_e32 v0, v5, v0
	s_nop 0
	s_waitcnt lgkmcnt(0)
	s_nop 1
	v_add_f32_dpp v0, v0, v0 quad_perm:[1,0,3,2] row_mask:0xf bank_mask:0xf
	s_nop 0
	s_waitcnt lgkmcnt(0)
	s_nop 1
	v_add_f32_dpp v0, v0, v0 quad_perm:[2,3,0,1] row_mask:0xf bank_mask:0xf
	s_nop 0
	s_waitcnt lgkmcnt(0)
	s_nop 1
	v_add_f32_dpp v0, v0, v0 row_half_mirror row_mask:0xf bank_mask:0xf
	s_nop 0
	s_waitcnt lgkmcnt(0)
	s_nop 1
	v_add_f32_dpp v0, v0, v0 row_mirror row_mask:0xf bank_mask:0xf
	v_mov_b32_e32 v4, v0
	s_nop 1
	v_permlane16_swap_b32_e32 v0, v4
	s_waitcnt lgkmcnt(0)
	v_add_f32_e32 v0, v0, v4
	v_mov_b32_e32 v4, v0
	s_nop 1
	v_permlane32_swap_b32_e32 v0, v4
	s_waitcnt lgkmcnt(0)
	v_add_f32_e32 v0, v0, v4
	v_fmamk_f32 v0, v0, 0x3b2aaaab, v162
	v_cmp_gt_f32_e64 s[42:43], s11, v0
	v_mul_f32_e32 v4, 0x4b800000, v0
	s_nop 0
	v_cndmask_b32_e64 v0, v0, v4, s[42:43]
	v_rsq_f32_e32 v0, v0
	s_nop 0
	v_mul_f32_e32 v4, 0x45800000, v0
	v_cndmask_b32_e64 v0, v0, v4, s[42:43]
	v_mul_f32_e32 v2, v2, v0
	v_fma_f32 v2, v14, v2, v20
	v_mul_f32_e32 v4, 0xbfb8aa3b, v2
	v_exp_f32_e32 v4, v4
	s_nop 0
	v_add_f32_e32 v4, 1.0, v4
	v_rcp_f32_e32 v4, v4
	s_nop 0
	v_mul_f32_e32 v4, v2, v4
	v_mul_f32_e32 v2, v3, v0
	v_fma_f32 v2, v15, v2, v21
	v_mul_f32_e32 v3, 0xbfb8aa3b, v2
	v_exp_f32_e32 v3, v3
	s_nop 0
	v_add_f32_e32 v3, 1.0, v3
	v_rcp_f32_e32 v3, v3
	s_nop 0
	v_mul_f32_e32 v5, v2, v3
	v_mul_f32_e32 v2, v8, v0
	v_fma_f32 v2, v16, v2, v22
	v_mul_f32_e32 v3, 0xbfb8aa3b, v2
	v_exp_f32_e32 v3, v3
	v_cvt_pk_bf16_f32 v4, v4, v5
	s_nop 0
	v_add_f32_e32 v3, 1.0, v3
	v_rcp_f32_e32 v3, v3
	s_nop 0
	v_mul_f32_e32 v6, v2, v3
	v_mul_f32_e32 v2, v9, v0
	v_fma_f32 v81, v17, v2, v23
	v_mul_f32_e32 v2, 0xbfb8aa3b, v81
	v_exp_f32_e32 v2, v2
	s_nop 0
	v_add_f32_e32 v2, 1.0, v2
	v_rcp_f32_e32 v2, v2
	s_nop 0
	v_mul_f32_e32 v7, v81, v2
	v_mul_f32_e32 v2, v82, v0
	v_mul_f32_e32 v0, v83, v0
	v_fma_f32 v2, v18, v2, v10
	v_fma_f32 v87, v19, v0, v11
	v_mul_f32_e32 v3, 0xbfb8aa3b, v2
	v_mul_f32_e32 v0, 0xbfb8aa3b, v87
	v_exp_f32_e32 v3, v3
	v_exp_f32_e32 v0, v0
	v_add_f32_e32 v3, 1.0, v3
	v_add_f32_e32 v0, 1.0, v0
	v_rcp_f32_e32 v3, v3
	v_rcp_f32_e32 v0, v0
	v_mul_f32_e32 v8, v2, v3
	v_mul_f32_e32 v0, v87, v0
	v_lshl_add_u64 v[2:3], v[76:77], 0, s[0:1]
	global_store_dword v[2:3], v4, off offset:1280
	v_cvt_pk_bf16_f32 v4, v6, v7
	global_store_dword v[2:3], v4, off offset:1284
	v_cvt_pk_bf16_f32 v0, v8, v0
	global_store_dword v[2:3], v0, off offset:1288
	s_cbranch_scc0 .LBB7_813
.LBB7_806:
	s_lshl_b32 s13, s12, 5
	s_waitcnt vmcnt(0)
	s_barrier
	s_and_saveexec_b64 s[0:1], vcc
	s_cbranch_execz .LBB7_811
	s_and_b32 s3, s13, 0x7e0
	s_sub_i32 s3, 29, s3
	v_lshl_add_u32 v78, v150, 5, 0
	s_mov_b32 s5, 0x2aaaaaab
	v_mov_b32_e32 v79, v150
	v_mul_hi_i32 v80, v79, s5
	v_lshrrev_b32_e32 v81, 31, v80
	v_ashrrev_i32_e32 v80, 3, v80
	v_add_u32_e32 v80, v80, v81
	v_cmp_lt_i32_e64 s[42:43], s3, v80
	s_nop 1
	v_mov_b64_e32 v[2:3], 0
	v_mov_b64_e32 v[4:5], 0
	v_mov_b64_e32 v[6:7], 0
	v_mov_b64_e32 v[8:9], 0
	s_and_saveexec_b64 s[8:9], s[42:43]
	v_lshlrev_b32_e32 v2, 16, v28
	v_and_b32_e32 v3, 0xffff0000, v28
	v_lshlrev_b32_e32 v4, 16, v29
	v_and_b32_e32 v5, 0xffff0000, v29
	v_lshlrev_b32_e32 v6, 16, v30
	v_and_b32_e32 v7, 0xffff0000, v30
	v_lshlrev_b32_e32 v8, 16, v31
	v_and_b32_e32 v9, 0xffff0000, v31
	v_mul_f32_e32 v2, 0xbfb8aa3b, v2
	v_mul_f32_e32 v3, 0xbfb8aa3b, v3
	v_mul_f32_e32 v4, 0xbfb8aa3b, v4
	v_mul_f32_e32 v5, 0xbfb8aa3b, v5
	v_mul_f32_e32 v6, 0xbfb8aa3b, v6
	v_mul_f32_e32 v7, 0xbfb8aa3b, v7
	v_mul_f32_e32 v8, 0xbfb8aa3b, v8
	v_mul_f32_e32 v9, 0xbfb8aa3b, v9
	v_exp_f32_e32 v2, v2
	v_exp_f32_e32 v3, v3
	v_exp_f32_e32 v4, v4
	v_exp_f32_e32 v5, v5
	v_exp_f32_e32 v6, v6
	v_exp_f32_e32 v7, v7
	v_exp_f32_e32 v8, v8
	v_exp_f32_e32 v9, v9
	v_add_f32_e32 v2, 1.0, v2
	v_add_f32_e32 v3, 1.0, v3
	v_add_f32_e32 v4, 1.0, v4
	v_add_f32_e32 v5, 1.0, v5
	v_add_f32_e32 v6, 1.0, v6
	v_add_f32_e32 v7, 1.0, v7
	v_add_f32_e32 v8, 1.0, v8
	v_add_f32_e32 v9, 1.0, v9
	v_rcp_f32_e32 v2, v2
	v_rcp_f32_e32 v3, v3
	v_rcp_f32_e32 v4, v4
	v_rcp_f32_e32 v5, v5
	v_rcp_f32_e32 v6, v6
	v_rcp_f32_e32 v7, v7
	v_rcp_f32_e32 v8, v8
	v_rcp_f32_e32 v9, v9
	v_lshlrev_b32_e32 v80, 16, v24
	v_and_b32_e32 v81, 0xffff0000, v24
	v_lshlrev_b32_e32 v82, 16, v25
	v_and_b32_e32 v83, 0xffff0000, v25
	v_lshlrev_b32_e32 v84, 16, v26
	v_and_b32_e32 v85, 0xffff0000, v26
	v_lshlrev_b32_e32 v86, 16, v27
	v_and_b32_e32 v87, 0xffff0000, v27
	v_mul_f32_e32 v2, v2, v80
	v_mul_f32_e32 v3, v3, v81
	v_mul_f32_e32 v4, v4, v82
	v_mul_f32_e32 v5, v5, v83
	v_mul_f32_e32 v6, v6, v84
	v_mul_f32_e32 v7, v7, v85
	v_mul_f32_e32 v8, v8, v86
	v_mul_f32_e32 v9, v9, v87
	s_or_b64 exec, exec, s[8:9]
	ds_write_b128 v78, v[2:5]
	ds_write_b128 v78, v[6:9] offset:16
	v_add_u32_e32 v79, 512, v150
	v_mul_hi_i32 v80, v79, s5
	v_lshrrev_b32_e32 v81, 31, v80
	v_ashrrev_i32_e32 v80, 3, v80
	v_add_u32_e32 v80, v80, v81
	v_cmp_lt_i32_e64 s[42:43], s3, v80
	s_nop 1
	v_mov_b64_e32 v[2:3], 0
	v_mov_b64_e32 v[4:5], 0
	v_mov_b64_e32 v[6:7], 0
	v_mov_b64_e32 v[8:9], 0
	s_and_saveexec_b64 s[8:9], s[42:43]
	v_lshlrev_b32_e32 v2, 16, v36
	v_and_b32_e32 v3, 0xffff0000, v36
	v_lshlrev_b32_e32 v4, 16, v37
	v_and_b32_e32 v5, 0xffff0000, v37
	v_lshlrev_b32_e32 v6, 16, v38
	v_and_b32_e32 v7, 0xffff0000, v38
	v_lshlrev_b32_e32 v8, 16, v39
	v_and_b32_e32 v9, 0xffff0000, v39
	v_mul_f32_e32 v2, 0xbfb8aa3b, v2
	v_mul_f32_e32 v3, 0xbfb8aa3b, v3
	v_mul_f32_e32 v4, 0xbfb8aa3b, v4
	v_mul_f32_e32 v5, 0xbfb8aa3b, v5
	v_mul_f32_e32 v6, 0xbfb8aa3b, v6
	v_mul_f32_e32 v7, 0xbfb8aa3b, v7
	v_mul_f32_e32 v8, 0xbfb8aa3b, v8
	v_mul_f32_e32 v9, 0xbfb8aa3b, v9
	v_exp_f32_e32 v2, v2
	v_exp_f32_e32 v3, v3
	v_exp_f32_e32 v4, v4
	v_exp_f32_e32 v5, v5
	v_exp_f32_e32 v6, v6
	v_exp_f32_e32 v7, v7
	v_exp_f32_e32 v8, v8
	v_exp_f32_e32 v9, v9
	v_add_f32_e32 v2, 1.0, v2
	v_add_f32_e32 v3, 1.0, v3
	v_add_f32_e32 v4, 1.0, v4
	v_add_f32_e32 v5, 1.0, v5
	v_add_f32_e32 v6, 1.0, v6
	v_add_f32_e32 v7, 1.0, v7
	v_add_f32_e32 v8, 1.0, v8
	v_add_f32_e32 v9, 1.0, v9
	v_rcp_f32_e32 v2, v2
	v_rcp_f32_e32 v3, v3
	v_rcp_f32_e32 v4, v4
	v_rcp_f32_e32 v5, v5
	v_rcp_f32_e32 v6, v6
	v_rcp_f32_e32 v7, v7
	v_rcp_f32_e32 v8, v8
	v_rcp_f32_e32 v9, v9
	v_lshlrev_b32_e32 v80, 16, v32
	v_and_b32_e32 v81, 0xffff0000, v32
	v_lshlrev_b32_e32 v82, 16, v33
	v_and_b32_e32 v83, 0xffff0000, v33
	v_lshlrev_b32_e32 v84, 16, v34
	v_and_b32_e32 v85, 0xffff0000, v34
	v_lshlrev_b32_e32 v86, 16, v35
	v_and_b32_e32 v87, 0xffff0000, v35
	v_mul_f32_e32 v2, v2, v80
	v_mul_f32_e32 v3, v3, v81
	v_mul_f32_e32 v4, v4, v82
	v_mul_f32_e32 v5, v5, v83
	v_mul_f32_e32 v6, v6, v84
	v_mul_f32_e32 v7, v7, v85
	v_mul_f32_e32 v8, v8, v86
	v_mul_f32_e32 v9, v9, v87
	s_or_b64 exec, exec, s[8:9]
	ds_write_b128 v78, v[2:5] offset:16384
	ds_write_b128 v78, v[6:9] offset:16400
	v_add_u32_e32 v79, 1024, v150
	v_mul_hi_i32 v80, v79, s5
	v_lshrrev_b32_e32 v81, 31, v80
	v_ashrrev_i32_e32 v80, 3, v80
	v_add_u32_e32 v80, v80, v81
	v_cmp_lt_i32_e64 s[42:43], s3, v80
	s_nop 1
	v_mov_b64_e32 v[2:3], 0
	v_mov_b64_e32 v[4:5], 0
	v_mov_b64_e32 v[6:7], 0
	v_mov_b64_e32 v[8:9], 0
	s_and_saveexec_b64 s[8:9], s[42:43]
	v_lshlrev_b32_e32 v2, 16, v44
	v_and_b32_e32 v3, 0xffff0000, v44
	v_lshlrev_b32_e32 v4, 16, v45
	v_and_b32_e32 v5, 0xffff0000, v45
	v_lshlrev_b32_e32 v6, 16, v46
	v_and_b32_e32 v7, 0xffff0000, v46
	v_lshlrev_b32_e32 v8, 16, v47
	v_and_b32_e32 v9, 0xffff0000, v47
	v_mul_f32_e32 v2, 0xbfb8aa3b, v2
	v_mul_f32_e32 v3, 0xbfb8aa3b, v3
	v_mul_f32_e32 v4, 0xbfb8aa3b, v4
	v_mul_f32_e32 v5, 0xbfb8aa3b, v5
	v_mul_f32_e32 v6, 0xbfb8aa3b, v6
	v_mul_f32_e32 v7, 0xbfb8aa3b, v7
	v_mul_f32_e32 v8, 0xbfb8aa3b, v8
	v_mul_f32_e32 v9, 0xbfb8aa3b, v9
	v_exp_f32_e32 v2, v2
	v_exp_f32_e32 v3, v3
	v_exp_f32_e32 v4, v4
	v_exp_f32_e32 v5, v5
	v_exp_f32_e32 v6, v6
	v_exp_f32_e32 v7, v7
	v_exp_f32_e32 v8, v8
	v_exp_f32_e32 v9, v9
	v_add_f32_e32 v2, 1.0, v2
	v_add_f32_e32 v3, 1.0, v3
	v_add_f32_e32 v4, 1.0, v4
	v_add_f32_e32 v5, 1.0, v5
	v_add_f32_e32 v6, 1.0, v6
	v_add_f32_e32 v7, 1.0, v7
	v_add_f32_e32 v8, 1.0, v8
	v_add_f32_e32 v9, 1.0, v9
	v_rcp_f32_e32 v2, v2
	v_rcp_f32_e32 v3, v3
	v_rcp_f32_e32 v4, v4
	v_rcp_f32_e32 v5, v5
	v_rcp_f32_e32 v6, v6
	v_rcp_f32_e32 v7, v7
	v_rcp_f32_e32 v8, v8
	v_rcp_f32_e32 v9, v9
	v_lshlrev_b32_e32 v80, 16, v40
	v_and_b32_e32 v81, 0xffff0000, v40
	v_lshlrev_b32_e32 v82, 16, v41
	v_and_b32_e32 v83, 0xffff0000, v41
	v_lshlrev_b32_e32 v84, 16, v42
	v_and_b32_e32 v85, 0xffff0000, v42
	v_lshlrev_b32_e32 v86, 16, v43
	v_and_b32_e32 v87, 0xffff0000, v43
	v_mul_f32_e32 v2, v2, v80
	v_mul_f32_e32 v3, v3, v81
	v_mul_f32_e32 v4, v4, v82
	v_mul_f32_e32 v5, v5, v83
	v_mul_f32_e32 v6, v6, v84
	v_mul_f32_e32 v7, v7, v85
	v_mul_f32_e32 v8, v8, v86
	v_mul_f32_e32 v9, v9, v87
	s_or_b64 exec, exec, s[8:9]
	ds_write_b128 v78, v[2:5] offset:32768
	ds_write_b128 v78, v[6:9] offset:32784
	v_add_u32_e32 v79, 1536, v150
	v_mul_hi_i32 v80, v79, s5
	v_lshrrev_b32_e32 v81, 31, v80
	v_ashrrev_i32_e32 v80, 3, v80
	v_add_u32_e32 v80, v80, v81
	v_cmp_lt_i32_e64 s[42:43], s3, v80
	s_nop 1
	v_mov_b64_e32 v[2:3], 0
	v_mov_b64_e32 v[4:5], 0
	v_mov_b64_e32 v[6:7], 0
	v_mov_b64_e32 v[8:9], 0
	s_and_saveexec_b64 s[8:9], s[42:43]
	v_lshlrev_b32_e32 v2, 16, v52
	v_and_b32_e32 v3, 0xffff0000, v52
	v_lshlrev_b32_e32 v4, 16, v53
	v_and_b32_e32 v5, 0xffff0000, v53
	v_lshlrev_b32_e32 v6, 16, v54
	v_and_b32_e32 v7, 0xffff0000, v54
	v_lshlrev_b32_e32 v8, 16, v55
	v_and_b32_e32 v9, 0xffff0000, v55
	v_mul_f32_e32 v2, 0xbfb8aa3b, v2
	v_mul_f32_e32 v3, 0xbfb8aa3b, v3
	v_mul_f32_e32 v4, 0xbfb8aa3b, v4
	v_mul_f32_e32 v5, 0xbfb8aa3b, v5
	v_mul_f32_e32 v6, 0xbfb8aa3b, v6
	v_mul_f32_e32 v7, 0xbfb8aa3b, v7
	v_mul_f32_e32 v8, 0xbfb8aa3b, v8
	v_mul_f32_e32 v9, 0xbfb8aa3b, v9
	v_exp_f32_e32 v2, v2
	v_exp_f32_e32 v3, v3
	v_exp_f32_e32 v4, v4
	v_exp_f32_e32 v5, v5
	v_exp_f32_e32 v6, v6
	v_exp_f32_e32 v7, v7
	v_exp_f32_e32 v8, v8
	v_exp_f32_e32 v9, v9
	v_add_f32_e32 v2, 1.0, v2
	v_add_f32_e32 v3, 1.0, v3
	v_add_f32_e32 v4, 1.0, v4
	v_add_f32_e32 v5, 1.0, v5
	v_add_f32_e32 v6, 1.0, v6
	v_add_f32_e32 v7, 1.0, v7
	v_add_f32_e32 v8, 1.0, v8
	v_add_f32_e32 v9, 1.0, v9
	v_rcp_f32_e32 v2, v2
	v_rcp_f32_e32 v3, v3
	v_rcp_f32_e32 v4, v4
	v_rcp_f32_e32 v5, v5
	v_rcp_f32_e32 v6, v6
	v_rcp_f32_e32 v7, v7
	v_rcp_f32_e32 v8, v8
	v_rcp_f32_e32 v9, v9
	v_lshlrev_b32_e32 v80, 16, v48
	v_and_b32_e32 v81, 0xffff0000, v48
	v_lshlrev_b32_e32 v82, 16, v49
	v_and_b32_e32 v83, 0xffff0000, v49
	v_lshlrev_b32_e32 v84, 16, v50
	v_and_b32_e32 v85, 0xffff0000, v50
	v_lshlrev_b32_e32 v86, 16, v51
	v_and_b32_e32 v87, 0xffff0000, v51
	v_mul_f32_e32 v2, v2, v80
	v_mul_f32_e32 v3, v3, v81
	v_mul_f32_e32 v4, v4, v82
	v_mul_f32_e32 v5, v5, v83
	v_mul_f32_e32 v6, v6, v84
	v_mul_f32_e32 v7, v7, v85
	v_mul_f32_e32 v8, v8, v86
	v_mul_f32_e32 v9, v9, v87
	s_or_b64 exec, exec, s[8:9]
	ds_write_b128 v78, v[2:5] offset:49152
	ds_write_b128 v78, v[6:9] offset:49168
	v_add_u32_e32 v79, 2048, v150
	v_mul_hi_i32 v80, v79, s5
	v_lshrrev_b32_e32 v81, 31, v80
	v_ashrrev_i32_e32 v80, 3, v80
	v_add_u32_e32 v80, v80, v81
	v_cmp_lt_i32_e64 s[42:43], s3, v80
	s_nop 1
	v_mov_b64_e32 v[2:3], 0
	v_mov_b64_e32 v[4:5], 0
	v_mov_b64_e32 v[6:7], 0
	v_mov_b64_e32 v[8:9], 0
	s_and_saveexec_b64 s[8:9], s[42:43]
	v_lshlrev_b32_e32 v2, 16, v60
	v_and_b32_e32 v3, 0xffff0000, v60
	v_lshlrev_b32_e32 v4, 16, v61
	v_and_b32_e32 v5, 0xffff0000, v61
	v_lshlrev_b32_e32 v6, 16, v62
	v_and_b32_e32 v7, 0xffff0000, v62
	v_lshlrev_b32_e32 v8, 16, v63
	v_and_b32_e32 v9, 0xffff0000, v63
	v_mul_f32_e32 v2, 0xbfb8aa3b, v2
	v_mul_f32_e32 v3, 0xbfb8aa3b, v3
	v_mul_f32_e32 v4, 0xbfb8aa3b, v4
	v_mul_f32_e32 v5, 0xbfb8aa3b, v5
	v_mul_f32_e32 v6, 0xbfb8aa3b, v6
	v_mul_f32_e32 v7, 0xbfb8aa3b, v7
	v_mul_f32_e32 v8, 0xbfb8aa3b, v8
	v_mul_f32_e32 v9, 0xbfb8aa3b, v9
	v_exp_f32_e32 v2, v2
	v_exp_f32_e32 v3, v3
	v_exp_f32_e32 v4, v4
	v_exp_f32_e32 v5, v5
	v_exp_f32_e32 v6, v6
	v_exp_f32_e32 v7, v7
	v_exp_f32_e32 v8, v8
	v_exp_f32_e32 v9, v9
	v_add_f32_e32 v2, 1.0, v2
	v_add_f32_e32 v3, 1.0, v3
	v_add_f32_e32 v4, 1.0, v4
	v_add_f32_e32 v5, 1.0, v5
	v_add_f32_e32 v6, 1.0, v6
	v_add_f32_e32 v7, 1.0, v7
	v_add_f32_e32 v8, 1.0, v8
	v_add_f32_e32 v9, 1.0, v9
	v_rcp_f32_e32 v2, v2
	v_rcp_f32_e32 v3, v3
	v_rcp_f32_e32 v4, v4
	v_rcp_f32_e32 v5, v5
	v_rcp_f32_e32 v6, v6
	v_rcp_f32_e32 v7, v7
	v_rcp_f32_e32 v8, v8
	v_rcp_f32_e32 v9, v9
	v_lshlrev_b32_e32 v80, 16, v56
	v_and_b32_e32 v81, 0xffff0000, v56
	v_lshlrev_b32_e32 v82, 16, v57
	v_and_b32_e32 v83, 0xffff0000, v57
	v_lshlrev_b32_e32 v84, 16, v58
	v_and_b32_e32 v85, 0xffff0000, v58
	v_lshlrev_b32_e32 v86, 16, v59
	v_and_b32_e32 v87, 0xffff0000, v59
	v_mul_f32_e32 v2, v2, v80
	v_mul_f32_e32 v3, v3, v81
	v_mul_f32_e32 v4, v4, v82
	v_mul_f32_e32 v5, v5, v83
	v_mul_f32_e32 v6, v6, v84
	v_mul_f32_e32 v7, v7, v85
	v_mul_f32_e32 v8, v8, v86
	v_mul_f32_e32 v9, v9, v87
	s_or_b64 exec, exec, s[8:9]
	v_add_u32_e32 v79, 0x10000, v78
	ds_write_b128 v79, v[2:5]
	ds_write_b128 v79, v[6:9] offset:16
	v_add_u32_e32 v79, 2560, v150
	v_mul_hi_i32 v80, v79, s5
	v_lshrrev_b32_e32 v81, 31, v80
	v_ashrrev_i32_e32 v80, 3, v80
	v_add_u32_e32 v80, v80, v81
	v_cmp_lt_i32_e64 s[42:43], s3, v80
	s_nop 1
	s_and_b64 s[42:43], s[42:43], s[6:7]
	v_mov_b64_e32 v[2:3], 0
	v_mov_b64_e32 v[4:5], 0
	v_mov_b64_e32 v[6:7], 0
	v_mov_b64_e32 v[8:9], 0
	s_and_saveexec_b64 s[8:9], s[42:43]
	v_lshlrev_b32_e32 v2, 16, v68
	v_and_b32_e32 v3, 0xffff0000, v68
	v_lshlrev_b32_e32 v4, 16, v69
	v_and_b32_e32 v5, 0xffff0000, v69
	v_lshlrev_b32_e32 v6, 16, v70
	v_and_b32_e32 v7, 0xffff0000, v70
	v_lshlrev_b32_e32 v8, 16, v71
	v_and_b32_e32 v9, 0xffff0000, v71
	v_mul_f32_e32 v2, 0xbfb8aa3b, v2
	v_mul_f32_e32 v3, 0xbfb8aa3b, v3
	v_mul_f32_e32 v4, 0xbfb8aa3b, v4
	v_mul_f32_e32 v5, 0xbfb8aa3b, v5
	v_mul_f32_e32 v6, 0xbfb8aa3b, v6
	v_mul_f32_e32 v7, 0xbfb8aa3b, v7
	v_mul_f32_e32 v8, 0xbfb8aa3b, v8
	v_mul_f32_e32 v9, 0xbfb8aa3b, v9
	v_exp_f32_e32 v2, v2
	v_exp_f32_e32 v3, v3
	v_exp_f32_e32 v4, v4
	v_exp_f32_e32 v5, v5
	v_exp_f32_e32 v6, v6
	v_exp_f32_e32 v7, v7
	v_exp_f32_e32 v8, v8
	v_exp_f32_e32 v9, v9
	v_add_f32_e32 v2, 1.0, v2
	v_add_f32_e32 v3, 1.0, v3
	v_add_f32_e32 v4, 1.0, v4
	v_add_f32_e32 v5, 1.0, v5
	v_add_f32_e32 v6, 1.0, v6
	v_add_f32_e32 v7, 1.0, v7
	v_add_f32_e32 v8, 1.0, v8
	v_add_f32_e32 v9, 1.0, v9
	v_rcp_f32_e32 v2, v2
	v_rcp_f32_e32 v3, v3
	v_rcp_f32_e32 v4, v4
	v_rcp_f32_e32 v5, v5
	v_rcp_f32_e32 v6, v6
	v_rcp_f32_e32 v7, v7
	v_rcp_f32_e32 v8, v8
	v_rcp_f32_e32 v9, v9
	v_lshlrev_b32_e32 v80, 16, v64
	v_and_b32_e32 v81, 0xffff0000, v64
	v_lshlrev_b32_e32 v82, 16, v65
	v_and_b32_e32 v83, 0xffff0000, v65
	v_lshlrev_b32_e32 v84, 16, v66
	v_and_b32_e32 v85, 0xffff0000, v66
	v_lshlrev_b32_e32 v86, 16, v67
	v_and_b32_e32 v87, 0xffff0000, v67
	v_mul_f32_e32 v2, v2, v80
	v_mul_f32_e32 v3, v3, v81
	v_mul_f32_e32 v4, v4, v82
	v_mul_f32_e32 v5, v5, v83
	v_mul_f32_e32 v6, v6, v84
	v_mul_f32_e32 v7, v7, v85
	v_mul_f32_e32 v8, v8, v86
	v_mul_f32_e32 v9, v9, v87
	s_or_b64 exec, exec, s[8:9]
	s_and_saveexec_b64 s[8:9], s[6:7]
	v_add_u32_e32 v79, 0x14000, v78
	ds_write_b128 v79, v[2:5]
	ds_write_b128 v79, v[6:9] offset:16
	s_or_b64 exec, exec, s[8:9]
.LBB7_811:
	s_or_b64 exec, exec, s[0:1]
	s_waitcnt lgkmcnt(0)
	s_barrier
	s_add_i32 s15, s12, s60
	s_cmpk_lt_i32 s15, 0x400
	s_cbranch_scc0 .Lcpf_skip
	s_movk_i32 s14, 0x1a0
	v_cmp_gt_i32_e64 s[6:7], s14, v150
	s_lshl_b32 s15, s15, 5
	s_and_b32 s3, s15, 0x7e0
	s_sub_i32 s3, 29, s3
	s_sub_i32 s4, s15, 30
	s_mov_b32 s5, 0x2aaaaaab
	s_movk_i32 s14, 0xfe80
	v_mov_b32_e32 v79, v150
	v_mul_hi_i32 v80, v79, s5
	v_lshrrev_b32_e32 v81, 31, v80
	v_ashrrev_i32_e32 v80, 3, v80
	v_add_u32_e32 v80, v80, v81
	v_cmp_lt_i32_e64 s[42:43], s3, v80
	s_nop 1
	s_and_saveexec_b64 s[8:9], s[42:43]
	v_add_u32_e32 v82, s4, v80
	v_ashrrev_i32_e32 v83, 31, v82
	v_lshlrev_b64 v[82:83], 11, v[82:83]
	v_lshl_add_u64 v[82:83], s[44:45], 0, v[82:83]
	v_lshlrev_b32_e32 v84, 3, v79
	v_mad_i32_i24 v84, v80, s14, v84
	v_mov_b32_e32 v85, 0
	v_lshl_add_u64 v[82:83], v[84:85], 1, v[82:83]
	global_load_dwordx4 v[24:27], v[82:83], off offset:512
	global_load_dwordx4 v[28:31], v[82:83], off offset:1280
	s_or_b64 exec, exec, s[8:9]
	v_add_u32_e32 v79, 512, v150
	v_mul_hi_i32 v80, v79, s5
	v_lshrrev_b32_e32 v81, 31, v80
	v_ashrrev_i32_e32 v80, 3, v80
	v_add_u32_e32 v80, v80, v81
	v_cmp_lt_i32_e64 s[42:43], s3, v80
	s_nop 1
	s_and_saveexec_b64 s[8:9], s[42:43]
	v_add_u32_e32 v82, s4, v80
	v_ashrrev_i32_e32 v83, 31, v82
	v_lshlrev_b64 v[82:83], 11, v[82:83]
	v_lshl_add_u64 v[82:83], s[44:45], 0, v[82:83]
	v_lshlrev_b32_e32 v84, 3, v79
	v_mad_i32_i24 v84, v80, s14, v84
	v_mov_b32_e32 v85, 0
	v_lshl_add_u64 v[82:83], v[84:85], 1, v[82:83]
	global_load_dwordx4 v[32:35], v[82:83], off offset:512
	global_load_dwordx4 v[36:39], v[82:83], off offset:1280
	s_or_b64 exec, exec, s[8:9]
	v_add_u32_e32 v79, 1024, v150
	v_mul_hi_i32 v80, v79, s5
	v_lshrrev_b32_e32 v81, 31, v80
	v_ashrrev_i32_e32 v80, 3, v80
	v_add_u32_e32 v80, v80, v81
	v_cmp_lt_i32_e64 s[42:43], s3, v80
	s_nop 1
	s_and_saveexec_b64 s[8:9], s[42:43]
	v_add_u32_e32 v82, s4, v80
	v_ashrrev_i32_e32 v83, 31, v82
	v_lshlrev_b64 v[82:83], 11, v[82:83]
	v_lshl_add_u64 v[82:83], s[44:45], 0, v[82:83]
	v_lshlrev_b32_e32 v84, 3, v79
	v_mad_i32_i24 v84, v80, s14, v84
	v_mov_b32_e32 v85, 0
	v_lshl_add_u64 v[82:83], v[84:85], 1, v[82:83]
	global_load_dwordx4 v[40:43], v[82:83], off offset:512
	global_load_dwordx4 v[44:47], v[82:83], off offset:1280
	s_or_b64 exec, exec, s[8:9]
	v_add_u32_e32 v79, 1536, v150
	v_mul_hi_i32 v80, v79, s5
	v_lshrrev_b32_e32 v81, 31, v80
	v_ashrrev_i32_e32 v80, 3, v80
	v_add_u32_e32 v80, v80, v81
	v_cmp_lt_i32_e64 s[42:43], s3, v80
	s_nop 1
	s_and_saveexec_b64 s[8:9], s[42:43]
	v_add_u32_e32 v82, s4, v80
	v_ashrrev_i32_e32 v83, 31, v82
	v_lshlrev_b64 v[82:83], 11, v[82:83]
	v_lshl_add_u64 v[82:83], s[44:45], 0, v[82:83]
	v_lshlrev_b32_e32 v84, 3, v79
	v_mad_i32_i24 v84, v80, s14, v84
	v_mov_b32_e32 v85, 0
	v_lshl_add_u64 v[82:83], v[84:85], 1, v[82:83]
	global_load_dwordx4 v[48:51], v[82:83], off offset:512
	global_load_dwordx4 v[52:55], v[82:83], off offset:1280
	s_or_b64 exec, exec, s[8:9]
	v_add_u32_e32 v79, 2048, v150
	v_mul_hi_i32 v80, v79, s5
	v_lshrrev_b32_e32 v81, 31, v80
	v_ashrrev_i32_e32 v80, 3, v80
	v_add_u32_e32 v80, v80, v81
	v_cmp_lt_i32_e64 s[42:43], s3, v80
	s_nop 1
	s_and_saveexec_b64 s[8:9], s[42:43]
	v_add_u32_e32 v82, s4, v80
	v_ashrrev_i32_e32 v83, 31, v82
	v_lshlrev_b64 v[82:83], 11, v[82:83]
	v_lshl_add_u64 v[82:83], s[44:45], 0, v[82:83]
	v_lshlrev_b32_e32 v84, 3, v79
	v_mad_i32_i24 v84, v80, s14, v84
	v_mov_b32_e32 v85, 0
	v_lshl_add_u64 v[82:83], v[84:85], 1, v[82:83]
	global_load_dwordx4 v[56:59], v[82:83], off offset:512
	global_load_dwordx4 v[60:63], v[82:83], off offset:1280
	s_or_b64 exec, exec, s[8:9]
	v_add_u32_e32 v79, 2560, v150
	v_mul_hi_i32 v80, v79, s5
	v_lshrrev_b32_e32 v81, 31, v80
	v_ashrrev_i32_e32 v80, 3, v80
	v_add_u32_e32 v80, v80, v81
	v_cmp_lt_i32_e64 s[42:43], s3, v80
	s_nop 1
	s_and_b64 s[42:43], s[42:43], s[6:7]
	s_and_saveexec_b64 s[8:9], s[42:43]
	v_add_u32_e32 v82, s4, v80
	v_ashrrev_i32_e32 v83, 31, v82
	v_lshlrev_b64 v[82:83], 11, v[82:83]
	v_lshl_add_u64 v[82:83], s[44:45], 0, v[82:83]
	v_lshlrev_b32_e32 v84, 3, v79
	v_mad_i32_i24 v84, v80, s14, v84
	v_mov_b32_e32 v85, 0
	v_lshl_add_u64 v[82:83], v[84:85], 1, v[82:83]
	global_load_dwordx4 v[64:67], v[82:83], off offset:512
	global_load_dwordx4 v[68:71], v[82:83], off offset:1280
	s_or_b64 exec, exec, s[8:9]
.Lcpf_skip:
	s_and_saveexec_b64 s[0:1], s[40:41]
	s_cbranch_execz .LBB7_805
	ds_read2st64_b32 v[170:171], v108 offset1:6
	ds_read2st64_b32 v[172:173], v108 offset0:12 offset1:18
	ds_read2st64_b32 v[106:107], v108 offset0:24 offset1:30
	ds_read2st64_b32 v[104:105], v108 offset0:36 offset1:42
	ds_read2st64_b32 v[102:103], v108 offset0:48 offset1:54
	ds_read2st64_b32 v[100:101], v108 offset0:60 offset1:66
	ds_read2st64_b32 v[98:99], v108 offset0:72 offset1:78
	ds_read2st64_b32 v[96:97], v108 offset0:84 offset1:90
	ds_read2st64_b32 v[94:95], v108 offset0:96 offset1:102
	ds_read2st64_b32 v[92:93], v108 offset0:108 offset1:114
	ds_read2st64_b32 v[90:91], v108 offset0:120 offset1:126
	ds_read2st64_b32 v[88:89], v108 offset0:132 offset1:138
	ds_read2st64_b32 v[86:87], v108 offset0:144 offset1:150
	ds_read2st64_b32 v[84:85], v108 offset0:156 offset1:162
	ds_read2st64_b32 v[82:83], v108 offset0:168 offset1:174
	ds_read2st64_b32 v[80:81], v108 offset0:180 offset1:186
	ds_read2st64_b32 v[78:79], v108 offset0:192 offset1:198
	ds_read2st64_b32 v[8:9], v108 offset0:204 offset1:210
	ds_read2st64_b32 v[6:7], v108 offset0:216 offset1:222
	ds_read2st64_b32 v[4:5], v108 offset0:228 offset1:234
	ds_read2st64_b32 v[2:3], v108 offset0:240 offset1:246
	ds_read_b32 v178, v108 offset:64512
	s_waitcnt lgkmcnt(14)
	v_fma_f32 v170, v216, v170, v247
	v_fma_f32 v179, v216, v171, v247
	v_fmac_f32_e32 v170, v217, v171
	v_fmac_f32_e32 v179, v217, v172
	v_fmac_f32_e32 v170, v218, v172
	v_fmac_f32_e32 v179, v218, v173
	v_fmac_f32_e32 v170, v219, v173
	v_fmac_f32_e32 v179, v219, v106
	v_fmac_f32_e32 v170, v220, v106
	v_fmac_f32_e32 v179, v220, v107
	v_fmac_f32_e32 v170, v221, v107
	v_fmac_f32_e32 v179, v221, v104
	v_fmac_f32_e32 v170, v222, v104
	v_fmac_f32_e32 v179, v222, v105
	v_fmac_f32_e32 v170, v223, v105
	v_fmac_f32_e32 v179, v223, v102
	v_fmac_f32_e32 v170, v224, v102
	v_fmac_f32_e32 v179, v224, v103
	v_fmac_f32_e32 v170, v225, v103
	v_fmac_f32_e32 v179, v225, v100
	v_fmac_f32_e32 v170, v226, v100
	v_fmac_f32_e32 v179, v226, v101
	v_fmac_f32_e32 v170, v227, v101
	v_fmac_f32_e32 v179, v227, v98
	v_fmac_f32_e32 v170, v228, v98
	v_fmac_f32_e32 v179, v228, v99
	v_fmac_f32_e32 v170, v229, v99
	v_fmac_f32_e32 v179, v229, v96
	v_fmac_f32_e32 v170, v230, v96
	v_fmac_f32_e32 v179, v230, v97
	v_fmac_f32_e32 v170, v231, v97
	s_waitcnt lgkmcnt(13)
	v_fmac_f32_e32 v179, v231, v94
	v_fmac_f32_e32 v170, v232, v94
	v_fmac_f32_e32 v179, v232, v95
	v_fmac_f32_e32 v170, v233, v95
	s_waitcnt lgkmcnt(12)
	v_fmac_f32_e32 v179, v233, v92
	v_fmac_f32_e32 v170, v234, v92
	v_fmac_f32_e32 v179, v234, v93
	v_fmac_f32_e32 v170, v235, v93
	s_waitcnt lgkmcnt(11)
	v_fmac_f32_e32 v179, v235, v90
	v_fmac_f32_e32 v170, v236, v90
	v_fmac_f32_e32 v179, v236, v91
	v_fmac_f32_e32 v170, v237, v91
	s_waitcnt lgkmcnt(10)
	v_fmac_f32_e32 v179, v237, v88
	v_fmac_f32_e32 v170, v238, v88
	v_fmac_f32_e32 v179, v238, v89
	v_fmac_f32_e32 v170, v239, v89
	s_waitcnt lgkmcnt(9)
	v_fmac_f32_e32 v179, v239, v86
	v_fmac_f32_e32 v170, v240, v86
	v_fmac_f32_e32 v179, v240, v87
	v_fmac_f32_e32 v170, v241, v87
	s_waitcnt lgkmcnt(8)
	v_fmac_f32_e32 v179, v241, v84
	v_fmac_f32_e32 v170, v242, v84
	v_fmac_f32_e32 v179, v242, v85
	v_fmac_f32_e32 v170, v243, v85
	s_waitcnt lgkmcnt(7)
	v_fmac_f32_e32 v179, v243, v82
	v_fmac_f32_e32 v170, v244, v82
	v_fmac_f32_e32 v179, v244, v83
	v_fmac_f32_e32 v170, v245, v83
	s_waitcnt lgkmcnt(6)
	v_fmac_f32_e32 v179, v245, v80
	v_fmac_f32_e32 v170, v246, v80
	v_fmac_f32_e32 v179, v246, v81
	ds_write2st64_b32 v109, v170, v179 offset1:6
	v_fma_f32 v170, v216, v172, v247
	v_fmac_f32_e32 v170, v217, v173
	v_fma_f32 v171, v216, v173, v247
	v_fmac_f32_e32 v170, v218, v106
	v_fmac_f32_e32 v171, v217, v106
	v_fma_f32 v106, v216, v106, v247
	v_fmac_f32_e32 v170, v219, v107
	v_fmac_f32_e32 v171, v218, v107
	v_fmac_f32_e32 v106, v217, v107
	v_fma_f32 v107, v216, v107, v247
	v_fmac_f32_e32 v107, v217, v104
	v_fmac_f32_e32 v106, v218, v104
	v_fmac_f32_e32 v107, v218, v105
	v_fmac_f32_e32 v106, v219, v105
	v_fmac_f32_e32 v107, v219, v102
	v_fmac_f32_e32 v106, v220, v102
	v_fmac_f32_e32 v107, v220, v103
	v_fmac_f32_e32 v106, v221, v103
	v_fmac_f32_e32 v107, v221, v100
	v_fmac_f32_e32 v106, v222, v100
	v_fmac_f32_e32 v107, v222, v101
	v_fmac_f32_e32 v106, v223, v101
	v_fmac_f32_e32 v107, v223, v98
	v_fmac_f32_e32 v106, v224, v98
	v_fmac_f32_e32 v107, v224, v99
	v_fmac_f32_e32 v106, v225, v99
	v_fmac_f32_e32 v107, v225, v96
	v_fmac_f32_e32 v106, v226, v96
	v_fmac_f32_e32 v107, v226, v97
	v_fmac_f32_e32 v106, v227, v97
	v_fmac_f32_e32 v107, v227, v94
	v_fmac_f32_e32 v106, v228, v94
	v_fmac_f32_e32 v107, v228, v95
	v_fmac_f32_e32 v106, v229, v95
	v_fmac_f32_e32 v107, v229, v92
	v_fmac_f32_e32 v106, v230, v92
	v_fmac_f32_e32 v107, v230, v93
	v_fmac_f32_e32 v106, v231, v93
	v_fmac_f32_e32 v107, v231, v90
	v_fmac_f32_e32 v106, v232, v90
	v_fmac_f32_e32 v107, v232, v91
	v_fmac_f32_e32 v106, v233, v91
	v_fmac_f32_e32 v107, v233, v88
	v_fmac_f32_e32 v106, v234, v88
	v_fmac_f32_e32 v107, v234, v89
	v_fmac_f32_e32 v106, v235, v89
	v_fmac_f32_e32 v107, v235, v86
	v_fmac_f32_e32 v106, v236, v86
	v_fmac_f32_e32 v107, v236, v87
	v_fmac_f32_e32 v106, v237, v87
	v_fmac_f32_e32 v107, v237, v84
	v_fmac_f32_e32 v106, v238, v84
	v_fmac_f32_e32 v107, v238, v85
	v_fmac_f32_e32 v106, v239, v85
	v_fmac_f32_e32 v107, v239, v82
	v_fmac_f32_e32 v170, v220, v104
	v_fmac_f32_e32 v171, v219, v104
	v_fmac_f32_e32 v106, v240, v82
	v_fmac_f32_e32 v107, v240, v83
	v_fma_f32 v104, v216, v104, v247
	v_fmac_f32_e32 v170, v221, v105
	v_fmac_f32_e32 v171, v220, v105
	v_fmac_f32_e32 v106, v241, v83
	v_fmac_f32_e32 v107, v241, v80
	v_fmac_f32_e32 v104, v217, v105
	v_fma_f32 v105, v216, v105, v247
	v_fmac_f32_e32 v170, v222, v102
	v_fmac_f32_e32 v171, v221, v102
	v_fmac_f32_e32 v106, v242, v80
	v_fmac_f32_e32 v107, v242, v81
	v_fmac_f32_e32 v104, v218, v102
	v_fmac_f32_e32 v105, v217, v102
	v_fma_f32 v102, v216, v102, v247
	v_fmac_f32_e32 v170, v223, v103
	v_fmac_f32_e32 v171, v222, v103
	v_fmac_f32_e32 v106, v243, v81
	s_waitcnt lgkmcnt(6)
	v_fmac_f32_e32 v107, v243, v78
	v_fmac_f32_e32 v104, v219, v103
	v_fmac_f32_e32 v105, v218, v103
	v_fmac_f32_e32 v102, v217, v103
	v_fma_f32 v103, v216, v103, v247
	v_fmac_f32_e32 v170, v224, v100
	v_fmac_f32_e32 v171, v223, v100
	v_fmac_f32_e32 v106, v244, v78
	v_fmac_f32_e32 v107, v244, v79
	v_fmac_f32_e32 v104, v220, v100
	v_fmac_f32_e32 v105, v219, v100
	v_fmac_f32_e32 v102, v218, v100
	v_fmac_f32_e32 v103, v217, v100
	v_fma_f32 v100, v216, v100, v247
	v_fmac_f32_e32 v170, v225, v101
	v_fmac_f32_e32 v171, v224, v101
	v_fmac_f32_e32 v106, v245, v79
	s_waitcnt lgkmcnt(5)
	v_fmac_f32_e32 v107, v245, v8
	v_fmac_f32_e32 v104, v221, v101
	v_fmac_f32_e32 v105, v220, v101
	v_fmac_f32_e32 v102, v219, v101
	v_fmac_f32_e32 v103, v218, v101
	v_fmac_f32_e32 v100, v217, v101
	v_fma_f32 v101, v216, v101, v247
	v_fmac_f32_e32 v106, v246, v8
	v_fmac_f32_e32 v107, v246, v9
	v_fmac_f32_e32 v101, v217, v98
	v_fmac_f32_e32 v170, v226, v98
	v_fmac_f32_e32 v171, v225, v98
	ds_write2st64_b32 v109, v106, v107 offset0:24 offset1:30
	v_fmac_f32_e32 v104, v222, v98
	v_fmac_f32_e32 v105, v221, v98
	v_fmac_f32_e32 v102, v220, v98
	v_fmac_f32_e32 v103, v219, v98
	v_fmac_f32_e32 v100, v218, v98
	v_fmac_f32_e32 v101, v218, v99
	v_fma_f32 v106, v216, v98, v247
	v_fmac_f32_e32 v170, v227, v99
	v_fmac_f32_e32 v171, v226, v99
	v_fmac_f32_e32 v104, v223, v99
	v_fmac_f32_e32 v105, v222, v99
	v_fmac_f32_e32 v102, v221, v99
	v_fmac_f32_e32 v103, v220, v99
	v_fmac_f32_e32 v100, v219, v99
	v_fmac_f32_e32 v101, v219, v96
	v_fmac_f32_e32 v106, v217, v99
	v_fma_f32 v107, v216, v99, v247
	v_fmac_f32_e32 v170, v228, v96
	v_fmac_f32_e32 v171, v227, v96
	v_fmac_f32_e32 v104, v224, v96
	v_fmac_f32_e32 v105, v223, v96
	v_fmac_f32_e32 v102, v222, v96
	v_fmac_f32_e32 v103, v221, v96
	v_fmac_f32_e32 v100, v220, v96
	v_fmac_f32_e32 v101, v220, v97
	v_fmac_f32_e32 v106, v218, v96
	v_fmac_f32_e32 v107, v217, v96
	v_fma_f32 v96, v216, v96, v247
	v_fmac_f32_e32 v170, v229, v97
	v_fmac_f32_e32 v171, v228, v97
	v_fmac_f32_e32 v104, v225, v97
	v_fmac_f32_e32 v105, v224, v97
	v_fmac_f32_e32 v102, v223, v97
	v_fmac_f32_e32 v103, v222, v97
	v_fmac_f32_e32 v100, v221, v97
	v_fmac_f32_e32 v101, v221, v94
	v_fmac_f32_e32 v106, v219, v97
	v_fmac_f32_e32 v107, v218, v97
	v_fmac_f32_e32 v96, v217, v97
	v_fma_f32 v97, v216, v97, v247
	v_fmac_f32_e32 v170, v230, v94
	v_fmac_f32_e32 v171, v229, v94
	v_fmac_f32_e32 v104, v226, v94
	v_fmac_f32_e32 v105, v225, v94
	v_fmac_f32_e32 v102, v224, v94
	v_fmac_f32_e32 v103, v223, v94
	v_fmac_f32_e32 v100, v222, v94
	v_fmac_f32_e32 v101, v222, v95
	v_fmac_f32_e32 v106, v220, v94
	v_fmac_f32_e32 v107, v219, v94
	v_fmac_f32_e32 v96, v218, v94
	v_fmac_f32_e32 v97, v217, v94
	v_fma_f32 v94, v216, v94, v247
	v_fmac_f32_e32 v170, v231, v95
	v_fmac_f32_e32 v171, v230, v95
	v_fmac_f32_e32 v104, v227, v95
	v_fmac_f32_e32 v105, v226, v95
	v_fmac_f32_e32 v102, v225, v95
	v_fmac_f32_e32 v103, v224, v95
	v_fmac_f32_e32 v100, v223, v95
	v_fmac_f32_e32 v101, v223, v92
	v_fmac_f32_e32 v106, v221, v95
	v_fmac_f32_e32 v107, v220, v95
	v_fmac_f32_e32 v96, v219, v95
	v_fmac_f32_e32 v97, v218, v95
	v_fmac_f32_e32 v94, v217, v95
	v_fma_f32 v95, v216, v95, v247
	v_fmac_f32_e32 v170, v232, v92
	v_fmac_f32_e32 v171, v231, v92
	v_fmac_f32_e32 v104, v228, v92
	v_fmac_f32_e32 v105, v227, v92
	v_fmac_f32_e32 v102, v226, v92
	v_fmac_f32_e32 v103, v225, v92
	v_fmac_f32_e32 v100, v224, v92
	v_fmac_f32_e32 v101, v224, v93
	v_fmac_f32_e32 v106, v222, v92
	v_fmac_f32_e32 v107, v221, v92
	v_fmac_f32_e32 v96, v220, v92
	v_fmac_f32_e32 v97, v219, v92
	v_fmac_f32_e32 v94, v218, v92
	v_fmac_f32_e32 v95, v217, v92
	v_fma_f32 v92, v216, v92, v247
	v_fmac_f32_e32 v170, v233, v93
	v_fmac_f32_e32 v171, v232, v93
	v_fmac_f32_e32 v104, v229, v93
	v_fmac_f32_e32 v105, v228, v93
	v_fmac_f32_e32 v102, v227, v93
	v_fmac_f32_e32 v103, v226, v93
	v_fmac_f32_e32 v100, v225, v93
	v_fmac_f32_e32 v101, v225, v90
	v_fmac_f32_e32 v106, v223, v93
	v_fmac_f32_e32 v107, v222, v93
	v_fmac_f32_e32 v96, v221, v93
	v_fmac_f32_e32 v97, v220, v93
	v_fmac_f32_e32 v94, v219, v93
	v_fmac_f32_e32 v95, v218, v93
	v_fmac_f32_e32 v92, v217, v93
	v_fma_f32 v93, v216, v93, v247
	v_fmac_f32_e32 v170, v234, v90
	v_fmac_f32_e32 v171, v233, v90
	v_fmac_f32_e32 v104, v230, v90
	v_fmac_f32_e32 v105, v229, v90
	v_fmac_f32_e32 v102, v228, v90
	v_fmac_f32_e32 v103, v227, v90
	v_fmac_f32_e32 v100, v226, v90
	v_fmac_f32_e32 v101, v226, v91
	v_fmac_f32_e32 v106, v224, v90
	v_fmac_f32_e32 v107, v223, v90
	v_fmac_f32_e32 v96, v222, v90
	v_fmac_f32_e32 v97, v221, v90
	v_fmac_f32_e32 v94, v220, v90
	v_fmac_f32_e32 v95, v219, v90
	v_fmac_f32_e32 v92, v218, v90
	v_fmac_f32_e32 v93, v217, v90
	v_fma_f32 v90, v216, v90, v247
	v_fmac_f32_e32 v170, v235, v91
	v_fmac_f32_e32 v171, v234, v91
	v_fmac_f32_e32 v104, v231, v91
	v_fmac_f32_e32 v105, v230, v91
	v_fmac_f32_e32 v102, v229, v91
	v_fmac_f32_e32 v103, v228, v91
	v_fmac_f32_e32 v100, v227, v91
	v_fmac_f32_e32 v101, v227, v88
	v_fmac_f32_e32 v106, v225, v91
	v_fmac_f32_e32 v107, v224, v91
	v_fmac_f32_e32 v96, v223, v91
	v_fmac_f32_e32 v97, v222, v91
	v_fmac_f32_e32 v94, v221, v91
	v_fmac_f32_e32 v95, v220, v91
	v_fmac_f32_e32 v92, v219, v91
	v_fmac_f32_e32 v93, v218, v91
	v_fmac_f32_e32 v90, v217, v91
	v_fma_f32 v91, v216, v91, v247
	v_fmac_f32_e32 v170, v236, v88
	v_fmac_f32_e32 v171, v235, v88
	v_fmac_f32_e32 v104, v232, v88
	v_fmac_f32_e32 v105, v231, v88
	v_fmac_f32_e32 v102, v230, v88
	v_fmac_f32_e32 v103, v229, v88
	v_fmac_f32_e32 v100, v228, v88
	v_fmac_f32_e32 v101, v228, v89
	v_fmac_f32_e32 v106, v226, v88
	v_fmac_f32_e32 v107, v225, v88
	v_fmac_f32_e32 v96, v224, v88
	v_fmac_f32_e32 v97, v223, v88
	v_fmac_f32_e32 v94, v222, v88
	v_fmac_f32_e32 v95, v221, v88
	v_fmac_f32_e32 v92, v220, v88
	v_fmac_f32_e32 v93, v219, v88
	v_fmac_f32_e32 v90, v218, v88
	v_fmac_f32_e32 v91, v217, v88
	v_fma_f32 v88, v216, v88, v247
	v_fmac_f32_e32 v170, v237, v89
	v_fmac_f32_e32 v171, v236, v89
	v_fmac_f32_e32 v104, v233, v89
	v_fmac_f32_e32 v105, v232, v89
	v_fmac_f32_e32 v102, v231, v89
	v_fmac_f32_e32 v103, v230, v89
	v_fmac_f32_e32 v100, v229, v89
	v_fmac_f32_e32 v101, v229, v86
	v_fmac_f32_e32 v106, v227, v89
	v_fmac_f32_e32 v107, v226, v89
	v_fmac_f32_e32 v96, v225, v89
	v_fmac_f32_e32 v97, v224, v89
	v_fmac_f32_e32 v94, v223, v89
	v_fmac_f32_e32 v95, v222, v89
	v_fmac_f32_e32 v92, v221, v89
	v_fmac_f32_e32 v93, v220, v89
	v_fmac_f32_e32 v90, v219, v89
	v_fmac_f32_e32 v91, v218, v89
	v_fmac_f32_e32 v88, v217, v89
	v_fma_f32 v89, v216, v89, v247
	v_fmac_f32_e32 v170, v238, v86
	v_fmac_f32_e32 v171, v237, v86
	v_fmac_f32_e32 v104, v234, v86
	v_fmac_f32_e32 v105, v233, v86
	v_fmac_f32_e32 v102, v232, v86
	v_fmac_f32_e32 v103, v231, v86
	v_fmac_f32_e32 v100, v230, v86
	v_fmac_f32_e32 v101, v230, v87
	v_fmac_f32_e32 v106, v228, v86
	v_fmac_f32_e32 v107, v227, v86
	v_fmac_f32_e32 v96, v226, v86
	v_fmac_f32_e32 v97, v225, v86
	v_fmac_f32_e32 v94, v224, v86
	v_fmac_f32_e32 v95, v223, v86
	v_fmac_f32_e32 v92, v222, v86
	v_fmac_f32_e32 v93, v221, v86
	v_fmac_f32_e32 v90, v220, v86
	v_fmac_f32_e32 v91, v219, v86
	v_fmac_f32_e32 v88, v218, v86
	v_fmac_f32_e32 v89, v217, v86
	v_fma_f32 v86, v216, v86, v247
	v_fmac_f32_e32 v170, v239, v87
	v_fmac_f32_e32 v171, v238, v87
	v_fmac_f32_e32 v104, v235, v87
	v_fmac_f32_e32 v105, v234, v87
	v_fmac_f32_e32 v102, v233, v87
	v_fmac_f32_e32 v103, v232, v87
	v_fmac_f32_e32 v100, v231, v87
	v_fmac_f32_e32 v101, v231, v84
	v_fmac_f32_e32 v106, v229, v87
	v_fmac_f32_e32 v107, v228, v87
	v_fmac_f32_e32 v96, v227, v87
	v_fmac_f32_e32 v97, v226, v87
	v_fmac_f32_e32 v94, v225, v87
	v_fmac_f32_e32 v95, v224, v87
	v_fmac_f32_e32 v92, v223, v87
	v_fmac_f32_e32 v93, v222, v87
	v_fmac_f32_e32 v90, v221, v87
	v_fmac_f32_e32 v91, v220, v87
	v_fmac_f32_e32 v88, v219, v87
	v_fmac_f32_e32 v89, v218, v87
	v_fmac_f32_e32 v86, v217, v87
	v_fma_f32 v87, v216, v87, v247
	v_fmac_f32_e32 v170, v240, v84
	v_fmac_f32_e32 v171, v239, v84
	v_fmac_f32_e32 v104, v236, v84
	v_fmac_f32_e32 v105, v235, v84
	v_fmac_f32_e32 v102, v234, v84
	v_fmac_f32_e32 v103, v233, v84
	v_fmac_f32_e32 v100, v232, v84
	v_fmac_f32_e32 v101, v232, v85
	v_fmac_f32_e32 v106, v230, v84
	v_fmac_f32_e32 v107, v229, v84
	v_fmac_f32_e32 v96, v228, v84
	v_fmac_f32_e32 v97, v227, v84
	v_fmac_f32_e32 v94, v226, v84
	v_fmac_f32_e32 v95, v225, v84
	v_fmac_f32_e32 v92, v224, v84
	v_fmac_f32_e32 v93, v223, v84
	v_fmac_f32_e32 v90, v222, v84
	v_fmac_f32_e32 v91, v221, v84
	v_fmac_f32_e32 v88, v220, v84
	v_fmac_f32_e32 v89, v219, v84
	v_fmac_f32_e32 v86, v218, v84
	v_fmac_f32_e32 v87, v217, v84
	v_fma_f32 v84, v216, v84, v247
	v_fmac_f32_e32 v170, v241, v85
	v_fmac_f32_e32 v171, v240, v85
	v_fmac_f32_e32 v104, v237, v85
	v_fmac_f32_e32 v105, v236, v85
	v_fmac_f32_e32 v102, v235, v85
	v_fmac_f32_e32 v103, v234, v85
	v_fmac_f32_e32 v100, v233, v85
	v_fmac_f32_e32 v101, v233, v82
	v_fmac_f32_e32 v106, v231, v85
	v_fmac_f32_e32 v107, v230, v85
	v_fmac_f32_e32 v96, v229, v85
	v_fmac_f32_e32 v97, v228, v85
	v_fmac_f32_e32 v94, v227, v85
	v_fmac_f32_e32 v95, v226, v85
	v_fmac_f32_e32 v92, v225, v85
	v_fmac_f32_e32 v93, v224, v85
	v_fmac_f32_e32 v90, v223, v85
	v_fmac_f32_e32 v91, v222, v85
	v_fmac_f32_e32 v88, v221, v85
	v_fmac_f32_e32 v89, v220, v85
	v_fmac_f32_e32 v86, v219, v85
	v_fmac_f32_e32 v87, v218, v85
	v_fmac_f32_e32 v84, v217, v85
	v_fma_f32 v85, v216, v85, v247
	v_fmac_f32_e32 v170, v242, v82
	v_fmac_f32_e32 v171, v241, v82
	v_fmac_f32_e32 v104, v238, v82
	v_fmac_f32_e32 v105, v237, v82
	v_fmac_f32_e32 v102, v236, v82
	v_fmac_f32_e32 v103, v235, v82
	v_fmac_f32_e32 v100, v234, v82
	v_fmac_f32_e32 v101, v234, v83
	v_fmac_f32_e32 v106, v232, v82
	v_fmac_f32_e32 v107, v231, v82
	v_fmac_f32_e32 v96, v230, v82
	v_fmac_f32_e32 v97, v229, v82
	v_fmac_f32_e32 v94, v228, v82
	v_fmac_f32_e32 v95, v227, v82
	v_fmac_f32_e32 v92, v226, v82
	v_fmac_f32_e32 v93, v225, v82
	v_fmac_f32_e32 v90, v224, v82
	v_fmac_f32_e32 v91, v223, v82
	v_fmac_f32_e32 v88, v222, v82
	v_fmac_f32_e32 v89, v221, v82
	v_fmac_f32_e32 v86, v220, v82
	v_fmac_f32_e32 v87, v219, v82
	v_fmac_f32_e32 v84, v218, v82
	v_fmac_f32_e32 v85, v217, v82
	v_fma_f32 v82, v216, v82, v247
	v_fmac_f32_e32 v170, v243, v83
	v_fmac_f32_e32 v171, v242, v83
	v_fmac_f32_e32 v104, v239, v83
	v_fmac_f32_e32 v105, v238, v83
	v_fmac_f32_e32 v102, v237, v83
	v_fmac_f32_e32 v103, v236, v83
	v_fmac_f32_e32 v100, v235, v83
	v_fmac_f32_e32 v101, v235, v80
	v_fmac_f32_e32 v106, v233, v83
	v_fmac_f32_e32 v107, v232, v83
	v_fmac_f32_e32 v96, v231, v83
	v_fmac_f32_e32 v97, v230, v83
	v_fmac_f32_e32 v94, v229, v83
	v_fmac_f32_e32 v95, v228, v83
	v_fmac_f32_e32 v92, v227, v83
	v_fmac_f32_e32 v93, v226, v83
	v_fmac_f32_e32 v90, v225, v83
	v_fmac_f32_e32 v91, v224, v83
	v_fmac_f32_e32 v88, v223, v83
	v_fmac_f32_e32 v89, v222, v83
	v_fmac_f32_e32 v86, v221, v83
	v_fmac_f32_e32 v87, v220, v83
	v_fmac_f32_e32 v84, v219, v83
	v_fmac_f32_e32 v85, v218, v83
	v_fmac_f32_e32 v82, v217, v83
	v_fma_f32 v83, v216, v83, v247
	v_fmac_f32_e32 v170, v244, v80
	v_fmac_f32_e32 v171, v243, v80
	v_fmac_f32_e32 v104, v240, v80
	v_fmac_f32_e32 v105, v239, v80
	v_fmac_f32_e32 v102, v238, v80
	v_fmac_f32_e32 v103, v237, v80
	v_fmac_f32_e32 v100, v236, v80
	v_fmac_f32_e32 v101, v236, v81
	v_fmac_f32_e32 v106, v234, v80
	v_fmac_f32_e32 v107, v233, v80
	v_fmac_f32_e32 v96, v232, v80
	v_fmac_f32_e32 v97, v231, v80
	v_fmac_f32_e32 v94, v230, v80
	v_fmac_f32_e32 v95, v229, v80
	v_fmac_f32_e32 v92, v228, v80
	v_fmac_f32_e32 v93, v227, v80
	v_fmac_f32_e32 v90, v226, v80
	v_fmac_f32_e32 v91, v225, v80
	v_fmac_f32_e32 v88, v224, v80
	v_fmac_f32_e32 v89, v223, v80
	v_fmac_f32_e32 v86, v222, v80
	v_fmac_f32_e32 v87, v221, v80
	v_fmac_f32_e32 v84, v220, v80
	v_fmac_f32_e32 v85, v219, v80
	v_fmac_f32_e32 v82, v218, v80
	v_fmac_f32_e32 v83, v217, v80
	v_fma_f32 v80, v216, v80, v247
	v_fma_f32 v0, v216, v81, v247
	v_fmac_f32_e32 v100, v237, v81
	v_fmac_f32_e32 v101, v237, v78
	v_fmac_f32_e32 v80, v217, v81
	v_fmac_f32_e32 v0, v217, v78
	v_fmac_f32_e32 v103, v238, v81
	v_fmac_f32_e32 v100, v238, v78
	v_fmac_f32_e32 v101, v238, v79
	v_fmac_f32_e32 v83, v218, v81
	v_fmac_f32_e32 v80, v218, v78
	v_fmac_f32_e32 v0, v218, v79
	v_fmac_f32_e32 v102, v239, v81
	v_fmac_f32_e32 v103, v239, v78
	v_fmac_f32_e32 v100, v239, v79
	v_fmac_f32_e32 v101, v239, v8
	v_fmac_f32_e32 v82, v219, v81
	v_fmac_f32_e32 v83, v219, v78
	v_fmac_f32_e32 v80, v219, v79
	v_fmac_f32_e32 v0, v219, v8
	v_fmac_f32_e32 v105, v240, v81
	v_fmac_f32_e32 v102, v240, v78
	v_fmac_f32_e32 v103, v240, v79
	v_fmac_f32_e32 v100, v240, v8
	v_fmac_f32_e32 v101, v240, v9
	v_fmac_f32_e32 v97, v232, v81
	v_fmac_f32_e32 v85, v220, v81
	v_fmac_f32_e32 v82, v220, v78
	v_fmac_f32_e32 v83, v220, v79
	v_fmac_f32_e32 v80, v220, v8
	v_fmac_f32_e32 v0, v220, v9
	v_fmac_f32_e32 v104, v241, v81
	v_fmac_f32_e32 v105, v241, v78
	v_fmac_f32_e32 v102, v241, v79
	v_fmac_f32_e32 v103, v241, v8
	v_fmac_f32_e32 v100, v241, v9
	s_waitcnt lgkmcnt(5)
	v_fmac_f32_e32 v101, v241, v6
	v_fmac_f32_e32 v96, v233, v81
	v_fmac_f32_e32 v97, v233, v78
	v_fmac_f32_e32 v84, v221, v81
	v_fmac_f32_e32 v85, v221, v78
	v_fmac_f32_e32 v82, v221, v79
	v_fmac_f32_e32 v83, v221, v8
	v_fmac_f32_e32 v80, v221, v9
	v_fmac_f32_e32 v0, v221, v6
	v_fmac_f32_e32 v104, v242, v78
	v_fmac_f32_e32 v105, v242, v79
	v_fmac_f32_e32 v102, v242, v8
	v_fmac_f32_e32 v103, v242, v9
	v_fmac_f32_e32 v100, v242, v6
	v_fmac_f32_e32 v101, v242, v7
	v_fmac_f32_e32 v107, v234, v81
	v_fmac_f32_e32 v96, v234, v78
	v_fmac_f32_e32 v97, v234, v79
	v_fmac_f32_e32 v87, v222, v81
	v_fmac_f32_e32 v84, v222, v78
	v_fmac_f32_e32 v85, v222, v79
	v_fmac_f32_e32 v82, v222, v8
	v_fmac_f32_e32 v83, v222, v9
	v_fmac_f32_e32 v80, v222, v6
	v_fmac_f32_e32 v0, v222, v7
	v_fmac_f32_e32 v104, v243, v79
	v_fmac_f32_e32 v105, v243, v8
	v_fmac_f32_e32 v102, v243, v9
	v_fmac_f32_e32 v103, v243, v6
	v_fmac_f32_e32 v100, v243, v7
	s_waitcnt lgkmcnt(4)
	v_fmac_f32_e32 v101, v243, v4
	v_fmac_f32_e32 v106, v235, v81
	v_fmac_f32_e32 v107, v235, v78
	v_fmac_f32_e32 v96, v235, v79
	v_fmac_f32_e32 v97, v235, v8
	v_fmac_f32_e32 v86, v223, v81
	v_fmac_f32_e32 v87, v223, v78
	v_fmac_f32_e32 v84, v223, v79
	v_fmac_f32_e32 v85, v223, v8
	v_fmac_f32_e32 v82, v223, v9
	v_fmac_f32_e32 v83, v223, v6
	v_fmac_f32_e32 v80, v223, v7
	v_fmac_f32_e32 v0, v223, v4
	v_fmac_f32_e32 v171, v244, v81
	v_fmac_f32_e32 v104, v244, v8
	v_fmac_f32_e32 v105, v244, v9
	v_fmac_f32_e32 v102, v244, v6
	v_fmac_f32_e32 v103, v244, v7
	v_fmac_f32_e32 v100, v244, v4
	v_fmac_f32_e32 v101, v244, v5
	v_fmac_f32_e32 v106, v236, v78
	v_fmac_f32_e32 v107, v236, v79
	v_fmac_f32_e32 v96, v236, v8
	v_fmac_f32_e32 v97, v236, v9
	v_fmac_f32_e32 v89, v224, v81
	v_fmac_f32_e32 v86, v224, v78
	v_fmac_f32_e32 v87, v224, v79
	v_fmac_f32_e32 v84, v224, v8
	v_fmac_f32_e32 v85, v224, v9
	v_fmac_f32_e32 v82, v224, v6
	v_fmac_f32_e32 v83, v224, v7
	v_fmac_f32_e32 v80, v224, v4
	v_fmac_f32_e32 v0, v224, v5
	v_fmac_f32_e32 v170, v245, v81
	v_fmac_f32_e32 v171, v245, v78
	v_fmac_f32_e32 v104, v245, v9
	v_fmac_f32_e32 v105, v245, v6
	v_fmac_f32_e32 v102, v245, v7
	v_fmac_f32_e32 v103, v245, v4
	v_fmac_f32_e32 v100, v245, v5
	s_waitcnt lgkmcnt(3)
	v_fmac_f32_e32 v101, v245, v2
	v_fmac_f32_e32 v106, v237, v79
	v_fmac_f32_e32 v107, v237, v8
	v_fmac_f32_e32 v96, v237, v9
	v_fmac_f32_e32 v97, v237, v6
	v_fmac_f32_e32 v88, v225, v81
	v_fmac_f32_e32 v89, v225, v78
	v_fmac_f32_e32 v86, v225, v79
	v_fmac_f32_e32 v87, v225, v8
	v_fmac_f32_e32 v84, v225, v9
	v_fmac_f32_e32 v85, v225, v6
	v_fmac_f32_e32 v82, v225, v7
	v_fmac_f32_e32 v83, v225, v4
	v_fmac_f32_e32 v80, v225, v5
	v_fmac_f32_e32 v0, v225, v2
	v_fmac_f32_e32 v170, v246, v78
	v_fmac_f32_e32 v171, v246, v79
	v_fmac_f32_e32 v104, v246, v6
	v_fmac_f32_e32 v105, v246, v7
	v_fmac_f32_e32 v102, v246, v4
	v_fmac_f32_e32 v103, v246, v5
	v_fmac_f32_e32 v100, v246, v2
	v_fmac_f32_e32 v101, v246, v3
	v_fmac_f32_e32 v106, v238, v8
	v_fmac_f32_e32 v107, v238, v9
	v_fmac_f32_e32 v96, v238, v6
	v_fmac_f32_e32 v97, v238, v7
	v_fmac_f32_e32 v91, v226, v81
	v_fmac_f32_e32 v88, v226, v78
	v_fmac_f32_e32 v89, v226, v79
	v_fmac_f32_e32 v86, v226, v8
	v_fmac_f32_e32 v87, v226, v9
	v_fmac_f32_e32 v84, v226, v6
	v_fmac_f32_e32 v85, v226, v7
	v_fmac_f32_e32 v82, v226, v4
	v_fmac_f32_e32 v83, v226, v5
	v_fmac_f32_e32 v80, v226, v2
	v_fmac_f32_e32 v0, v226, v3
	ds_write2st64_b32 v109, v170, v171 offset0:12 offset1:18
	ds_write2st64_b32 v109, v104, v105 offset0:36 offset1:42
	ds_write2st64_b32 v109, v102, v103 offset0:48 offset1:54
	ds_write2st64_b32 v109, v100, v101 offset0:60 offset1:66
	v_fmac_f32_e32 v106, v239, v9
	v_fmac_f32_e32 v107, v239, v6
	v_fmac_f32_e32 v96, v239, v7
	v_fmac_f32_e32 v97, v239, v4
	v_fmac_f32_e32 v90, v227, v81
	v_fmac_f32_e32 v91, v227, v78
	v_fmac_f32_e32 v88, v227, v79
	v_fmac_f32_e32 v89, v227, v8
	v_fmac_f32_e32 v86, v227, v9
	v_fmac_f32_e32 v87, v227, v6
	v_fmac_f32_e32 v84, v227, v7
	v_fmac_f32_e32 v85, v227, v4
	v_fmac_f32_e32 v82, v227, v5
	v_fmac_f32_e32 v83, v227, v2
	v_fmac_f32_e32 v80, v227, v3
	s_waitcnt lgkmcnt(6)
	v_fmac_f32_e32 v0, v227, v178
	v_fmac_f32_e32 v106, v240, v6
	v_fmac_f32_e32 v107, v240, v7
	ds_read_b32 v100, v115
	ds_read_b32 v99, v116
	ds_read_b32 v98, v117
	ds_read_b32 v105, v118
	ds_read_b32 v104, v119
	ds_read_b32 v103, v120
	ds_read_b32 v102, v121
	ds_read_b32 v101, v122
	v_fmac_f32_e32 v96, v240, v4
	v_fmac_f32_e32 v97, v240, v5
	v_fmac_f32_e32 v93, v228, v81
	v_fmac_f32_e32 v90, v228, v78
	v_fmac_f32_e32 v91, v228, v79
	v_fmac_f32_e32 v88, v228, v8
	v_fmac_f32_e32 v89, v228, v9
	v_fmac_f32_e32 v86, v228, v6
	v_fmac_f32_e32 v87, v228, v7
	v_fmac_f32_e32 v84, v228, v4
	v_fmac_f32_e32 v85, v228, v5
	v_fmac_f32_e32 v82, v228, v2
	v_fmac_f32_e32 v83, v228, v3
	v_fmac_f32_e32 v80, v228, v178
	s_waitcnt lgkmcnt(7)
	v_fmac_f32_e32 v0, v228, v100
	v_fmac_f32_e32 v106, v241, v7
	v_fmac_f32_e32 v107, v241, v4
	v_fmac_f32_e32 v96, v241, v5
	v_fmac_f32_e32 v97, v241, v2
	v_fmac_f32_e32 v92, v229, v81
	v_fmac_f32_e32 v93, v229, v78
	v_fmac_f32_e32 v90, v229, v79
	v_fmac_f32_e32 v91, v229, v8
	v_fmac_f32_e32 v88, v229, v9
	v_fmac_f32_e32 v89, v229, v6
	v_fmac_f32_e32 v86, v229, v7
	v_fmac_f32_e32 v87, v229, v4
	v_fmac_f32_e32 v84, v229, v5
	v_fmac_f32_e32 v85, v229, v2
	v_fmac_f32_e32 v82, v229, v3
	v_fmac_f32_e32 v83, v229, v178
	v_fmac_f32_e32 v80, v229, v100
	s_waitcnt lgkmcnt(6)
	v_fmac_f32_e32 v0, v229, v99
	v_fmac_f32_e32 v106, v242, v4
	v_fmac_f32_e32 v107, v242, v5
	v_fmac_f32_e32 v96, v242, v2
	v_fmac_f32_e32 v97, v242, v3
	v_fmac_f32_e32 v95, v230, v81
	v_fmac_f32_e32 v92, v230, v78
	v_fmac_f32_e32 v93, v230, v79
	v_fmac_f32_e32 v90, v230, v8
	v_fmac_f32_e32 v91, v230, v9
	v_fmac_f32_e32 v88, v230, v6
	v_fmac_f32_e32 v89, v230, v7
	v_fmac_f32_e32 v86, v230, v4
	v_fmac_f32_e32 v87, v230, v5
	v_fmac_f32_e32 v84, v230, v2
	v_fmac_f32_e32 v85, v230, v3
	v_fmac_f32_e32 v82, v230, v178
	v_fmac_f32_e32 v83, v230, v100
	v_fmac_f32_e32 v80, v230, v99
	s_waitcnt lgkmcnt(5)
	v_fmac_f32_e32 v0, v230, v98
	v_fmac_f32_e32 v106, v243, v5
	v_fmac_f32_e32 v107, v243, v2
	v_fmac_f32_e32 v96, v243, v3
	v_fmac_f32_e32 v97, v243, v178
	v_fmac_f32_e32 v94, v231, v81
	v_fmac_f32_e32 v95, v231, v78
	v_fmac_f32_e32 v92, v231, v79
	v_fmac_f32_e32 v93, v231, v8
	v_fmac_f32_e32 v90, v231, v9
	v_fmac_f32_e32 v91, v231, v6
	v_fmac_f32_e32 v88, v231, v7
	v_fmac_f32_e32 v89, v231, v4
	v_fmac_f32_e32 v86, v231, v5
	v_fmac_f32_e32 v87, v231, v2
	v_fmac_f32_e32 v84, v231, v3
	v_fmac_f32_e32 v85, v231, v178
	v_fmac_f32_e32 v82, v231, v100
	v_fmac_f32_e32 v83, v231, v99
	v_fmac_f32_e32 v80, v231, v98
	s_waitcnt lgkmcnt(4)
	v_fmac_f32_e32 v0, v231, v105
	v_fmac_f32_e32 v106, v244, v2
	v_fmac_f32_e32 v107, v244, v3
	v_fmac_f32_e32 v96, v244, v178
	v_fmac_f32_e32 v97, v244, v100
	v_fmac_f32_e32 v94, v232, v78
	v_fmac_f32_e32 v95, v232, v79
	v_fmac_f32_e32 v92, v232, v8
	v_fmac_f32_e32 v93, v232, v9
	v_fmac_f32_e32 v90, v232, v6
	v_fmac_f32_e32 v91, v232, v7
	v_fmac_f32_e32 v88, v232, v4
	v_fmac_f32_e32 v89, v232, v5
	v_fmac_f32_e32 v86, v232, v2
	v_fmac_f32_e32 v87, v232, v3
	v_fmac_f32_e32 v84, v232, v178
	v_fmac_f32_e32 v85, v232, v100
	v_fmac_f32_e32 v82, v232, v99
	v_fmac_f32_e32 v83, v232, v98
	v_fmac_f32_e32 v80, v232, v105
	s_waitcnt lgkmcnt(3)
	v_fmac_f32_e32 v0, v232, v104
	v_fmac_f32_e32 v106, v245, v3
	v_fmac_f32_e32 v107, v245, v178
	v_fmac_f32_e32 v96, v245, v100
	v_fmac_f32_e32 v97, v245, v99
	v_fmac_f32_e32 v94, v233, v79
	v_fmac_f32_e32 v95, v233, v8
	v_fmac_f32_e32 v92, v233, v9
	v_fmac_f32_e32 v93, v233, v6
	v_fmac_f32_e32 v90, v233, v7
	v_fmac_f32_e32 v91, v233, v4
	v_fmac_f32_e32 v88, v233, v5
	v_fmac_f32_e32 v89, v233, v2
	v_fmac_f32_e32 v86, v233, v3
	v_fmac_f32_e32 v87, v233, v178
	v_fmac_f32_e32 v84, v233, v100
	v_fmac_f32_e32 v85, v233, v99
	v_fmac_f32_e32 v82, v233, v98
	v_fmac_f32_e32 v83, v233, v105
	v_fmac_f32_e32 v80, v233, v104
	s_waitcnt lgkmcnt(2)
	v_fmac_f32_e32 v0, v233, v103
	v_fmac_f32_e32 v106, v246, v178
	v_fmac_f32_e32 v107, v246, v100
	v_fmac_f32_e32 v96, v246, v99
	v_fmac_f32_e32 v97, v246, v98
	v_fmac_f32_e32 v94, v234, v8
	v_fmac_f32_e32 v95, v234, v9
	v_fmac_f32_e32 v92, v234, v6
	v_fmac_f32_e32 v93, v234, v7
	v_fmac_f32_e32 v90, v234, v4
	v_fmac_f32_e32 v91, v234, v5
	v_fmac_f32_e32 v88, v234, v2
	v_fmac_f32_e32 v89, v234, v3
	v_fmac_f32_e32 v86, v234, v178
	v_fmac_f32_e32 v87, v234, v100
	v_fmac_f32_e32 v84, v234, v99
	v_fmac_f32_e32 v85, v234, v98
	v_fmac_f32_e32 v82, v234, v105
	v_fmac_f32_e32 v83, v234, v104
	v_fmac_f32_e32 v80, v234, v103
	s_waitcnt lgkmcnt(1)
	v_fmac_f32_e32 v0, v234, v102
	ds_write2st64_b32 v109, v106, v107 offset0:72 offset1:78
	ds_write2st64_b32 v109, v96, v97 offset0:84 offset1:90
	v_fmac_f32_e32 v94, v235, v9
	v_fmac_f32_e32 v95, v235, v6
	v_fmac_f32_e32 v92, v235, v7
	v_fmac_f32_e32 v93, v235, v4
	v_fmac_f32_e32 v90, v235, v5
	v_fmac_f32_e32 v91, v235, v2
	v_fmac_f32_e32 v88, v235, v3
	v_fmac_f32_e32 v89, v235, v178
	v_fmac_f32_e32 v86, v235, v100
	v_fmac_f32_e32 v87, v235, v99
	v_fmac_f32_e32 v84, v235, v98
	v_fmac_f32_e32 v85, v235, v105
	v_fmac_f32_e32 v82, v235, v104
	v_fmac_f32_e32 v83, v235, v103
	v_fmac_f32_e32 v80, v235, v102
	s_waitcnt lgkmcnt(2)
	v_fmac_f32_e32 v0, v235, v101
	ds_read_b32 v185, v123
	ds_read_b32 v184, v124
	ds_read_b32 v183, v125
	ds_read_b32 v182, v126
	ds_read_b32 v181, v127
	ds_read_b32 v180, v128
	ds_read_b32 v179, v129
	ds_read_b32 v107, v130
	ds_read_b32 v106, v131
	ds_read_b32 v97, v132
	ds_read_b32 v96, v133
	v_fmac_f32_e32 v94, v236, v6
	v_fmac_f32_e32 v95, v236, v7
	v_fmac_f32_e32 v92, v236, v4
	v_fmac_f32_e32 v93, v236, v5
	v_fmac_f32_e32 v90, v236, v2
	v_fmac_f32_e32 v91, v236, v3
	v_fmac_f32_e32 v88, v236, v178
	v_fmac_f32_e32 v89, v236, v100
	v_fmac_f32_e32 v86, v236, v99
	v_fmac_f32_e32 v87, v236, v98
	v_fmac_f32_e32 v84, v236, v105
	v_fmac_f32_e32 v85, v236, v104
	v_fmac_f32_e32 v82, v236, v103
	v_fmac_f32_e32 v83, v236, v102
	v_fmac_f32_e32 v80, v236, v101
	s_waitcnt lgkmcnt(10)
	v_fmac_f32_e32 v0, v236, v185
	v_fmac_f32_e32 v94, v237, v7
	v_fmac_f32_e32 v95, v237, v4
	v_fmac_f32_e32 v92, v237, v5
	v_fmac_f32_e32 v93, v237, v2
	v_fmac_f32_e32 v90, v237, v3
	v_fmac_f32_e32 v91, v237, v178
	v_fmac_f32_e32 v88, v237, v100
	v_fmac_f32_e32 v89, v237, v99
	v_fmac_f32_e32 v86, v237, v98
	v_fmac_f32_e32 v87, v237, v105
	v_fmac_f32_e32 v84, v237, v104
	v_fmac_f32_e32 v85, v237, v103
	v_fmac_f32_e32 v82, v237, v102
	v_fmac_f32_e32 v83, v237, v101
	v_fmac_f32_e32 v80, v237, v185
	s_waitcnt lgkmcnt(9)
	v_fmac_f32_e32 v0, v237, v184
	v_fmac_f32_e32 v94, v238, v4
	v_fmac_f32_e32 v95, v238, v5
	v_fmac_f32_e32 v92, v238, v2
	v_fmac_f32_e32 v93, v238, v3
	v_fmac_f32_e32 v90, v238, v178
	v_fmac_f32_e32 v91, v238, v100
	v_fmac_f32_e32 v88, v238, v99
	v_fmac_f32_e32 v89, v238, v98
	v_fmac_f32_e32 v86, v238, v105
	v_fmac_f32_e32 v87, v238, v104
	v_fmac_f32_e32 v84, v238, v103
	v_fmac_f32_e32 v85, v238, v102
	v_fmac_f32_e32 v82, v238, v101
	v_fmac_f32_e32 v83, v238, v185
	v_fmac_f32_e32 v80, v238, v184
	s_waitcnt lgkmcnt(8)
	v_fmac_f32_e32 v0, v238, v183
	v_fmac_f32_e32 v94, v239, v5
	v_fmac_f32_e32 v95, v239, v2
	v_fmac_f32_e32 v92, v239, v3
	v_fmac_f32_e32 v93, v239, v178
	v_fmac_f32_e32 v90, v239, v100
	v_fmac_f32_e32 v91, v239, v99
	v_fmac_f32_e32 v88, v239, v98
	v_fmac_f32_e32 v89, v239, v105
	v_fmac_f32_e32 v86, v239, v104
	v_fmac_f32_e32 v87, v239, v103
	v_fmac_f32_e32 v84, v239, v102
	v_fmac_f32_e32 v85, v239, v101
	v_fmac_f32_e32 v82, v239, v185
	v_fmac_f32_e32 v83, v239, v184
	v_fmac_f32_e32 v80, v239, v183
	s_waitcnt lgkmcnt(7)
	v_fmac_f32_e32 v0, v239, v182
	v_fmac_f32_e32 v94, v240, v2
	v_fmac_f32_e32 v95, v240, v3
	v_fmac_f32_e32 v92, v240, v178
	v_fmac_f32_e32 v93, v240, v100
	v_fmac_f32_e32 v90, v240, v99
	v_fmac_f32_e32 v91, v240, v98
	v_fmac_f32_e32 v88, v240, v105
	v_fmac_f32_e32 v89, v240, v104
	v_fmac_f32_e32 v86, v240, v103
	v_fmac_f32_e32 v87, v240, v102
	v_fmac_f32_e32 v84, v240, v101
	v_fmac_f32_e32 v85, v240, v185
	v_fmac_f32_e32 v82, v240, v184
	v_fmac_f32_e32 v83, v240, v183
	v_fmac_f32_e32 v80, v240, v182
	s_waitcnt lgkmcnt(6)
	v_fmac_f32_e32 v0, v240, v181
	v_fmac_f32_e32 v94, v241, v3
	v_fmac_f32_e32 v95, v241, v178
	v_fmac_f32_e32 v92, v241, v100
	v_fmac_f32_e32 v93, v241, v99
	v_fmac_f32_e32 v90, v241, v98
	v_fmac_f32_e32 v91, v241, v105
	v_fmac_f32_e32 v88, v241, v104
	v_fmac_f32_e32 v89, v241, v103
	v_fmac_f32_e32 v86, v241, v102
	v_fmac_f32_e32 v87, v241, v101
	v_fmac_f32_e32 v84, v241, v185
	v_fmac_f32_e32 v85, v241, v184
	v_fmac_f32_e32 v82, v241, v183
	v_fmac_f32_e32 v83, v241, v182
	v_fmac_f32_e32 v80, v241, v181
	s_waitcnt lgkmcnt(5)
	v_fmac_f32_e32 v0, v241, v180
	v_fmac_f32_e32 v94, v242, v178
	v_fmac_f32_e32 v95, v242, v100
	v_fmac_f32_e32 v92, v242, v99
	v_fmac_f32_e32 v93, v242, v98
	v_fmac_f32_e32 v90, v242, v105
	v_fmac_f32_e32 v91, v242, v104
	v_fmac_f32_e32 v88, v242, v103
	v_fmac_f32_e32 v89, v242, v102
	v_fmac_f32_e32 v86, v242, v101
	v_fmac_f32_e32 v87, v242, v185
	v_fmac_f32_e32 v84, v242, v184
	v_fmac_f32_e32 v85, v242, v183
	v_fmac_f32_e32 v82, v242, v182
	v_fmac_f32_e32 v83, v242, v181
	v_fmac_f32_e32 v80, v242, v180
	s_waitcnt lgkmcnt(4)
	v_fmac_f32_e32 v0, v242, v179
	v_fmac_f32_e32 v94, v243, v100
	v_fmac_f32_e32 v95, v243, v99
	v_fmac_f32_e32 v92, v243, v98
	v_fmac_f32_e32 v93, v243, v105
	v_fmac_f32_e32 v90, v243, v104
	v_fmac_f32_e32 v91, v243, v103
	v_fmac_f32_e32 v88, v243, v102
	v_fmac_f32_e32 v89, v243, v101
	v_fmac_f32_e32 v86, v243, v185
	v_fmac_f32_e32 v87, v243, v184
	v_fmac_f32_e32 v84, v243, v183
	v_fmac_f32_e32 v85, v243, v182
	v_fmac_f32_e32 v82, v243, v181
	v_fmac_f32_e32 v83, v243, v180
	v_fmac_f32_e32 v80, v243, v179
	s_waitcnt lgkmcnt(3)
	v_fmac_f32_e32 v0, v243, v107
	v_fmac_f32_e32 v94, v244, v99
	v_fmac_f32_e32 v95, v244, v98
	v_fmac_f32_e32 v92, v244, v105
	v_fmac_f32_e32 v93, v244, v104
	v_fmac_f32_e32 v90, v244, v103
	v_fmac_f32_e32 v91, v244, v102
	v_fmac_f32_e32 v88, v244, v101
	v_fmac_f32_e32 v89, v244, v185
	v_fmac_f32_e32 v86, v244, v184
	v_fmac_f32_e32 v87, v244, v183
	v_fmac_f32_e32 v84, v244, v182
	v_fmac_f32_e32 v85, v244, v181
	v_fmac_f32_e32 v82, v244, v180
	v_fmac_f32_e32 v83, v244, v179
	v_fmac_f32_e32 v80, v244, v107
	s_waitcnt lgkmcnt(2)
	v_fmac_f32_e32 v0, v244, v106
	v_fmac_f32_e32 v94, v245, v98
	v_fmac_f32_e32 v95, v245, v105
	v_fmac_f32_e32 v92, v245, v104
	v_fmac_f32_e32 v93, v245, v103
	v_fmac_f32_e32 v90, v245, v102
	v_fmac_f32_e32 v91, v245, v101
	v_fmac_f32_e32 v88, v245, v185
	v_fmac_f32_e32 v89, v245, v184
	v_fmac_f32_e32 v86, v245, v183
	v_fmac_f32_e32 v87, v245, v182
	v_fmac_f32_e32 v84, v245, v181
	v_fmac_f32_e32 v85, v245, v180
	v_fmac_f32_e32 v82, v245, v179
	v_fmac_f32_e32 v83, v245, v107
	v_fmac_f32_e32 v80, v245, v106
	s_waitcnt lgkmcnt(1)
	v_fmac_f32_e32 v0, v245, v97
	v_fmac_f32_e32 v94, v246, v105
	v_fmac_f32_e32 v95, v246, v104
	v_fmac_f32_e32 v92, v246, v103
	v_fmac_f32_e32 v93, v246, v102
	v_fmac_f32_e32 v90, v246, v101
	v_fmac_f32_e32 v91, v246, v185
	v_fmac_f32_e32 v88, v246, v184
	v_fmac_f32_e32 v89, v246, v183
	v_fmac_f32_e32 v86, v246, v182
	v_fmac_f32_e32 v87, v246, v181
	v_fmac_f32_e32 v84, v246, v180
	v_fmac_f32_e32 v85, v246, v179
	v_fmac_f32_e32 v82, v246, v107
	v_fmac_f32_e32 v83, v246, v106
	v_fmac_f32_e32 v80, v246, v97
	s_waitcnt lgkmcnt(0)
	v_fmac_f32_e32 v0, v246, v96
	ds_write2st64_b32 v109, v94, v95 offset0:96 offset1:102
	ds_write2st64_b32 v109, v92, v93 offset0:108 offset1:114
	ds_write2st64_b32 v109, v90, v91 offset0:120 offset1:126
	ds_write2st64_b32 v109, v88, v89 offset0:132 offset1:138
	ds_write2st64_b32 v109, v86, v87 offset0:144 offset1:150
	ds_write2st64_b32 v109, v84, v85 offset0:156 offset1:162
	ds_write2st64_b32 v109, v82, v83 offset0:168 offset1:174
	ds_write2st64_b32 v109, v80, v0 offset0:180 offset1:186
	s_branch .LBB7_805
